# V6 + GEMM K-loops: mid-block s_setprio 0/1 flip pairs removed (A/B)
# baseline (speedup 1.0000x reference)
; #define PG8_STAGE(bufoff, gbase, voff) do { _Pragma("unroll") for (int _i = 0; _i < 2; ++_i) \
;         __builtin_amdgcn_global_load_lds((const unsigned*)((const char*)(gbase) + (voff)[_i]), (PG8_LAS unsigned*)(lds + (bufoff) + ldsw + _i * 8192), 16, 0, 0); } while (0)
; #define PG8_LDA(dst, b, h) do { _Pragma("unroll") for (int m = 0; m < 4; ++m) _Pragma("unroll") for (int k = 0; k < 2; ++k) dst[m][k] = *(const PG8_LAS bf16x8*)(lds + PG8_SA(b, h) + aoff + m * 2048 + k * 1024); } while (0)
; #define PG8_LDB(dst, b, h) do { _Pragma("unroll") for (int n = 0; n < 2; ++n) _Pragma("unroll") for (int k = 0; k < 2; ++k) dst[n][k] = *(const PG8_LAS bf16x8*)(lds + PG8_SB(b, h) + boff + n * 2048 + k * 1024); } while (0)
; #define PG8_MMA(ai, bj, At, Bt) do { __builtin_amdgcn_s_setprio(1); _Pragma("unroll") for (int m = 0; m < 4; ++m) _Pragma("unroll") for (int n = 0; n < 2; ++n) _Pragma("unroll") for (int k = 0; k < 2; ++k) \
;         acc[ai][bj][m][n] = __builtin_amdgcn_mfma_f32_16x16x32_bf16(Bt[n][k], At[m][k], acc[ai][bj][m][n], 0, 0, 0); __builtin_amdgcn_s_setprio(0); } while (0)
; #define PG8_WAIT_V(n) asm volatile("s_waitcnt vmcnt(" #n ")" ::: "memory")
; #define PG8_WAIT_L(n) asm volatile("s_waitcnt lgkmcnt(" #n ")" ::: "memory")
; #define PG8_BAR __builtin_amdgcn_s_barrier()
; #define PG8_SCHED __builtin_amdgcn_sched_barrier(0)
; template <class Epi, class Sched, bool ALIGN_EPI = false, bool SP2 = false>
; __device__ __forceinline__ void gemm_phase(PG8_LAS unsigned char* lds, const Gemm g, const Sched& S, const Epi& E, int tid_in) {
;     ...
;             PG8_LDB(B0, 0, 0); PG8_LDB(B1, 0, 1); PG8_SCHED; PG8_LDA(At, 0, 0); PG8_STAGE(PG8_SA(1, 1), a1 + hstep, voffA);
;             PG8_WAIT_V(8); PG8_WAIT_L(0); PG8_BAR; PG8_MMA(0, 0, At, B0); PG8_MMA(0, 1, At, B1); PG8_BAR; PG8_SCHED;
;             PG8_LDA(At, 0, 1); PG8_STAGE(PG8_SB(0, 0), b2, voffB); PG8_STAGE(PG8_SB(0, 1), b2 + hstep, voffB); PG8_STAGE(PG8_SA(0, 0), a2, voffA);
;             PG8_WAIT_V(8); PG8_WAIT_L(0); PG8_BAR; PG8_MMA(1, 0, At, B0); PG8_MMA(1, 1, At, B1); PG8_BAR; PG8_SCHED;
.LBB0_376:
	s_add_u32 s26, s24, 0xfffc0080
	s_addc_u32 s27, s25, -1
	s_cmp_eq_u32 s56, 12
	s_cselect_b32 s29, s17, s27
	s_cselect_b32 s28, s52, s26
	s_cselect_b32 s27, s15, s55
	s_cselect_b32 s26, s53, s54
	s_add_i32 m0, s23, 0xc000
	ds_read_b128 v[150:153], v147
	global_load_lds_dwordx4 v136, s[24:25]
	s_add_i32 m0, s23, 0xe000
	ds_read_b128 v[154:157], v147 offset:1024
	global_load_lds_dwordx4 v138, s[24:25]
	ds_read_b128 v[158:161], v147 offset:2048
	ds_read_b128 v[162:165], v147 offset:3072
	ds_read_b128 v[166:169], v148
	ds_read_b128 v[170:173], v148 offset:1024
	ds_read_b128 v[174:177], v148 offset:2048
	ds_read_b128 v[178:181], v148 offset:3072
	ds_read_b128 v[182:185], v149
	ds_read_b128 v[186:189], v149 offset:1024
	ds_read_b128 v[190:193], v149 offset:2048
	ds_read_b128 v[194:197], v149 offset:3072
	ds_read_b128 v[198:201], v149 offset:4096
	ds_read_b128 v[202:205], v149 offset:5120
	ds_read_b128 v[206:209], v149 offset:6144
	ds_read_b128 v[210:213], v149 offset:7168
	s_waitcnt vmcnt(8)
	s_waitcnt lgkmcnt(0)
	s_barrier
	s_setprio 1
	v_mfma_f32_16x16x32_bf16 v[124:127], v[150:153], v[182:185], v[124:127]
	v_mfma_f32_16x16x32_bf16 v[120:123], v[158:161], v[182:185], v[120:123]
	v_mfma_f32_16x16x32_bf16 v[108:111], v[150:153], v[190:193], v[108:111]
	v_mfma_f32_16x16x32_bf16 v[104:107], v[158:161], v[190:193], v[104:107]
	v_mfma_f32_16x16x32_bf16 v[92:95], v[150:153], v[198:201], v[92:95]
	v_mfma_f32_16x16x32_bf16 v[88:91], v[158:161], v[198:201], v[88:91]
	v_mfma_f32_16x16x32_bf16 v[76:79], v[150:153], v[206:209], v[76:79]
	v_mfma_f32_16x16x32_bf16 v[72:75], v[158:161], v[206:209], v[72:75]
	v_mfma_f32_16x16x32_bf16 v[124:127], v[154:157], v[186:189], v[124:127]
	v_mfma_f32_16x16x32_bf16 v[120:123], v[162:165], v[186:189], v[120:123]
	v_mfma_f32_16x16x32_bf16 v[108:111], v[154:157], v[194:197], v[108:111]
	v_mfma_f32_16x16x32_bf16 v[104:107], v[162:165], v[194:197], v[104:107]
	v_mfma_f32_16x16x32_bf16 v[92:95], v[154:157], v[202:205], v[92:95]
	v_mfma_f32_16x16x32_bf16 v[88:91], v[162:165], v[202:205], v[88:91]
	v_mfma_f32_16x16x32_bf16 v[76:79], v[154:157], v[210:213], v[76:79]
	v_mfma_f32_16x16x32_bf16 v[72:75], v[162:165], v[210:213], v[72:75]
	v_mfma_f32_16x16x32_bf16 v[116:119], v[166:169], v[182:185], v[116:119]
	v_mfma_f32_16x16x32_bf16 v[112:115], v[174:177], v[182:185], v[112:115]
	v_mfma_f32_16x16x32_bf16 v[100:103], v[166:169], v[190:193], v[100:103]
	v_mfma_f32_16x16x32_bf16 v[96:99], v[174:177], v[190:193], v[96:99]
	v_mfma_f32_16x16x32_bf16 v[84:87], v[166:169], v[198:201], v[84:87]
	v_mfma_f32_16x16x32_bf16 v[80:83], v[174:177], v[198:201], v[80:83]
	v_mfma_f32_16x16x32_bf16 v[68:71], v[166:169], v[206:209], v[68:71]
	v_mfma_f32_16x16x32_bf16 v[64:67], v[174:177], v[206:209], v[64:67]
	v_mfma_f32_16x16x32_bf16 v[116:119], v[170:173], v[186:189], v[116:119]
	v_mfma_f32_16x16x32_bf16 v[112:115], v[178:181], v[186:189], v[112:115]
	v_mfma_f32_16x16x32_bf16 v[100:103], v[170:173], v[194:197], v[100:103]
	v_mfma_f32_16x16x32_bf16 v[96:99], v[178:181], v[194:197], v[96:99]
	v_mfma_f32_16x16x32_bf16 v[84:87], v[170:173], v[202:205], v[84:87]
	v_mfma_f32_16x16x32_bf16 v[80:83], v[178:181], v[202:205], v[80:83]
	v_mfma_f32_16x16x32_bf16 v[68:71], v[170:173], v[210:213], v[68:71]
	v_mfma_f32_16x16x32_bf16 v[64:67], v[178:181], v[210:213], v[64:67]
	s_setprio 0
	s_barrier
	s_add_u32 s98, s26, s10
	s_addc_u32 s99, s27, s11
	s_add_u32 s100, s28, s10
	s_addc_u32 s101, s29, s11
	s_add_i32 s57, s48, s34
	s_mov_b32 m0, s57
	ds_read_b128 v[182:185], v149 offset:16384
	global_load_lds_dwordx4 v132, s[26:27]
	s_add_i32 m0, s57, 0x2000
	s_add_u32 s60, s26, 0x40000
	s_addc_u32 s61, s27, 0
	s_add_i32 s57, s49, s34
	global_load_lds_dwordx4 v128, s[26:27]
	s_mov_b32 m0, s57
	ds_read_b128 v[186:189], v149 offset:17408
	global_load_lds_dwordx4 v132, s[60:61]
	s_add_i32 m0, s57, 0x2000
	ds_read_b128 v[190:193], v149 offset:18432
	global_load_lds_dwordx4 v128, s[60:61]
	s_mov_b32 m0, s23
	ds_read_b128 v[194:197], v149 offset:19456
	global_load_lds_dwordx4 v134, s[28:29]
	s_mov_b32 m0, s37
	ds_read_b128 v[198:201], v149 offset:20480
	global_load_lds_dwordx4 v130, s[28:29]
	ds_read_b128 v[202:205], v149 offset:21504
	ds_read_b128 v[206:209], v149 offset:22528
	ds_read_b128 v[210:213], v149 offset:23552
	s_waitcnt vmcnt(8)
	s_waitcnt lgkmcnt(0)
	s_barrier
	s_setprio 1
	v_mfma_f32_16x16x32_bf16 v[60:63], v[150:153], v[182:185], v[60:63]
	v_mfma_f32_16x16x32_bf16 v[56:59], v[158:161], v[182:185], v[56:59]
	v_mfma_f32_16x16x32_bf16 v[44:47], v[150:153], v[190:193], v[44:47]
	v_mfma_f32_16x16x32_bf16 v[40:43], v[158:161], v[190:193], v[40:43]
	v_mfma_f32_16x16x32_bf16 v[28:31], v[150:153], v[198:201], v[28:31]
	v_mfma_f32_16x16x32_bf16 v[24:27], v[158:161], v[198:201], v[24:27]
	v_mfma_f32_16x16x32_bf16 v[12:15], v[150:153], v[206:209], v[12:15]
	v_mfma_f32_16x16x32_bf16 v[8:11], v[158:161], v[206:209], v[8:11]
	v_mfma_f32_16x16x32_bf16 v[60:63], v[154:157], v[186:189], v[60:63]
	v_mfma_f32_16x16x32_bf16 v[56:59], v[162:165], v[186:189], v[56:59]
	v_mfma_f32_16x16x32_bf16 v[44:47], v[154:157], v[194:197], v[44:47]
	v_mfma_f32_16x16x32_bf16 v[40:43], v[162:165], v[194:197], v[40:43]
	v_mfma_f32_16x16x32_bf16 v[28:31], v[154:157], v[202:205], v[28:31]
	v_mfma_f32_16x16x32_bf16 v[24:27], v[162:165], v[202:205], v[24:27]
	v_mfma_f32_16x16x32_bf16 v[12:15], v[154:157], v[210:213], v[12:15]
	v_mfma_f32_16x16x32_bf16 v[8:11], v[162:165], v[210:213], v[8:11]
	v_mfma_f32_16x16x32_bf16 v[52:55], v[166:169], v[182:185], v[52:55]
	v_mfma_f32_16x16x32_bf16 v[48:51], v[174:177], v[182:185], v[48:51]
	v_mfma_f32_16x16x32_bf16 v[36:39], v[166:169], v[190:193], v[36:39]
	v_mfma_f32_16x16x32_bf16 v[32:35], v[174:177], v[190:193], v[32:35]
	v_mfma_f32_16x16x32_bf16 v[20:23], v[166:169], v[198:201], v[20:23]
	v_mfma_f32_16x16x32_bf16 v[16:19], v[174:177], v[198:201], v[16:19]
	v_mfma_f32_16x16x32_bf16 v[4:7], v[166:169], v[206:209], v[4:7]
	v_mfma_f32_16x16x32_bf16 v[0:3], v[174:177], v[206:209], v[0:3]
	v_mfma_f32_16x16x32_bf16 v[52:55], v[170:173], v[186:189], v[52:55]
	v_mfma_f32_16x16x32_bf16 v[48:51], v[178:181], v[186:189], v[48:51]
	v_mfma_f32_16x16x32_bf16 v[36:39], v[170:173], v[194:197], v[36:39]
	v_mfma_f32_16x16x32_bf16 v[32:35], v[178:181], v[194:197], v[32:35]
	v_mfma_f32_16x16x32_bf16 v[20:23], v[170:173], v[202:205], v[20:23]
	v_mfma_f32_16x16x32_bf16 v[16:19], v[178:181], v[202:205], v[16:19]
	v_mfma_f32_16x16x32_bf16 v[4:7], v[170:173], v[210:213], v[4:7]
	v_mfma_f32_16x16x32_bf16 v[0:3], v[178:181], v[210:213], v[0:3]
	s_setprio 0
	s_barrier
; #define PG8_STAGE(bufoff, gbase, voff) do { _Pragma("unroll") for (int _i = 0; _i < 2; ++_i) \
;         __builtin_amdgcn_global_load_lds((const unsigned*)((const char*)(gbase) + (voff)[_i]), (PG8_LAS unsigned*)(lds + (bufoff) + ldsw + _i * 8192), 16, 0, 0); } while (0)
; #define PG8_LDA(dst, b, h) do { _Pragma("unroll") for (int m = 0; m < 4; ++m) _Pragma("unroll") for (int k = 0; k < 2; ++k) dst[m][k] = *(const PG8_LAS bf16x8*)(lds + PG8_SA(b, h) + aoff + m * 2048 + k * 1024); } while (0)
; #define PG8_LDB(dst, b, h) do { _Pragma("unroll") for (int n = 0; n < 2; ++n) _Pragma("unroll") for (int k = 0; k < 2; ++k) dst[n][k] = *(const PG8_LAS bf16x8*)(lds + PG8_SB(b, h) + boff + n * 2048 + k * 1024); } while (0)
; #define PG8_MMA(ai, bj, At, Bt) do { __builtin_amdgcn_s_setprio(1); _Pragma("unroll") for (int m = 0; m < 4; ++m) _Pragma("unroll") for (int n = 0; n < 2; ++n) _Pragma("unroll") for (int k = 0; k < 2; ++k) \
;         acc[ai][bj][m][n] = __builtin_amdgcn_mfma_f32_16x16x32_bf16(Bt[n][k], At[m][k], acc[ai][bj][m][n], 0, 0, 0); __builtin_amdgcn_s_setprio(0); } while (0)
; #define PG8_WAIT_V(n) asm volatile("s_waitcnt vmcnt(" #n ")" ::: "memory")
; #define PG8_WAIT_L(n) asm volatile("s_waitcnt lgkmcnt(" #n ")" ::: "memory")
; #define PG8_BAR __builtin_amdgcn_s_barrier()
; #define PG8_SCHED __builtin_amdgcn_sched_barrier(0)
; template <class Epi, class Sched, bool ALIGN_EPI = false, bool SP2 = false>
; __device__ __forceinline__ void gemm_phase(PG8_LAS unsigned char* lds, const Gemm g, const Sched& S, const Epi& E, int tid_in) {
;     ...
;             PG8_LDB(B0, 1, 0); PG8_LDB(B1, 1, 1); PG8_SCHED; PG8_LDA(At, 1, 0); PG8_STAGE(PG8_SA(0, 1), a2 + hstep, voffA);
;             PG8_WAIT_V(8); PG8_WAIT_L(0); PG8_BAR; PG8_MMA(0, 0, At, B0); PG8_MMA(0, 1, At, B1); PG8_BAR; PG8_SCHED;
;             PG8_LDA(At, 1, 1); PG8_STAGE(PG8_SB(1, 0), b3, voffB); PG8_STAGE(PG8_SB(1, 1), b3 + hstep, voffB); PG8_STAGE(PG8_SA(1, 0), a3, voffA);
;             PG8_WAIT_V(8); PG8_WAIT_L(0); PG8_BAR; PG8_MMA(1, 0, At, B0); PG8_MMA(1, 1, At, B1); PG8_BAR; PG8_SCHED;
	s_add_i32 s57, 0, 0x18000
	s_add_i32 s59, 0, 0x1c000
	s_add_u32 s28, s28, 0x40000
	s_addc_u32 s29, s29, 0
	s_mov_b32 m0, s38
	s_nop 0
	global_load_lds_dwordx4 v134, s[28:29]
	s_mov_b32 m0, s39
	s_nop 0
	global_load_lds_dwordx4 v130, s[28:29]
	v_add_u32_e32 v162, s57, v145
	v_add_u32_e32 v178, s59, v145
	ds_read_b128 v[150:153], v162
	ds_read_b128 v[154:157], v162 offset:1024
	ds_read_b128 v[158:161], v162 offset:2048
	ds_read_b128 v[162:165], v162 offset:3072
	ds_read_b128 v[166:169], v178
	ds_read_b128 v[170:173], v178 offset:1024
	ds_read_b128 v[174:177], v178 offset:2048
	ds_read_b128 v[178:181], v178 offset:3072
	ds_read_b128 v[182:185], v149 offset:32768
	ds_read_b128 v[186:189], v149 offset:33792
	ds_read_b128 v[190:193], v149 offset:34816
	ds_read_b128 v[194:197], v149 offset:35840
	ds_read_b128 v[198:201], v149 offset:36864
	ds_read_b128 v[202:205], v149 offset:37888
	ds_read_b128 v[206:209], v149 offset:38912
	ds_read_b128 v[210:213], v149 offset:39936
	s_waitcnt vmcnt(8)
	s_waitcnt lgkmcnt(0)
	s_barrier
	s_setprio 1
	v_mfma_f32_16x16x32_bf16 v[124:127], v[150:153], v[182:185], v[124:127]
	v_mfma_f32_16x16x32_bf16 v[120:123], v[158:161], v[182:185], v[120:123]
	v_mfma_f32_16x16x32_bf16 v[108:111], v[150:153], v[190:193], v[108:111]
	v_mfma_f32_16x16x32_bf16 v[104:107], v[158:161], v[190:193], v[104:107]
	v_mfma_f32_16x16x32_bf16 v[92:95], v[150:153], v[198:201], v[92:95]
	v_mfma_f32_16x16x32_bf16 v[88:91], v[158:161], v[198:201], v[88:91]
	v_mfma_f32_16x16x32_bf16 v[76:79], v[150:153], v[206:209], v[76:79]
	v_mfma_f32_16x16x32_bf16 v[72:75], v[158:161], v[206:209], v[72:75]
	v_mfma_f32_16x16x32_bf16 v[124:127], v[154:157], v[186:189], v[124:127]
	v_mfma_f32_16x16x32_bf16 v[120:123], v[162:165], v[186:189], v[120:123]
	v_mfma_f32_16x16x32_bf16 v[108:111], v[154:157], v[194:197], v[108:111]
	v_mfma_f32_16x16x32_bf16 v[104:107], v[162:165], v[194:197], v[104:107]
	v_mfma_f32_16x16x32_bf16 v[92:95], v[154:157], v[202:205], v[92:95]
	v_mfma_f32_16x16x32_bf16 v[88:91], v[162:165], v[202:205], v[88:91]
	v_mfma_f32_16x16x32_bf16 v[76:79], v[154:157], v[210:213], v[76:79]
	v_mfma_f32_16x16x32_bf16 v[72:75], v[162:165], v[210:213], v[72:75]
	v_mfma_f32_16x16x32_bf16 v[116:119], v[166:169], v[182:185], v[116:119]
	v_mfma_f32_16x16x32_bf16 v[112:115], v[174:177], v[182:185], v[112:115]
	v_mfma_f32_16x16x32_bf16 v[100:103], v[166:169], v[190:193], v[100:103]
	v_mfma_f32_16x16x32_bf16 v[96:99], v[174:177], v[190:193], v[96:99]
	v_mfma_f32_16x16x32_bf16 v[84:87], v[166:169], v[198:201], v[84:87]
	v_mfma_f32_16x16x32_bf16 v[80:83], v[174:177], v[198:201], v[80:83]
	v_mfma_f32_16x16x32_bf16 v[68:71], v[166:169], v[206:209], v[68:71]
	v_mfma_f32_16x16x32_bf16 v[64:67], v[174:177], v[206:209], v[64:67]
	v_mfma_f32_16x16x32_bf16 v[116:119], v[170:173], v[186:189], v[116:119]
	v_mfma_f32_16x16x32_bf16 v[112:115], v[178:181], v[186:189], v[112:115]
	v_mfma_f32_16x16x32_bf16 v[100:103], v[170:173], v[194:197], v[100:103]
	v_mfma_f32_16x16x32_bf16 v[96:99], v[178:181], v[194:197], v[96:99]
	v_mfma_f32_16x16x32_bf16 v[84:87], v[170:173], v[202:205], v[84:87]
	v_mfma_f32_16x16x32_bf16 v[80:83], v[178:181], v[202:205], v[80:83]
	v_mfma_f32_16x16x32_bf16 v[68:71], v[170:173], v[210:213], v[68:71]
	v_mfma_f32_16x16x32_bf16 v[64:67], v[178:181], v[210:213], v[64:67]
	s_setprio 0
	s_barrier
	s_add_i32 s28, s57, s34
	s_mov_b32 m0, s28
	ds_read_b128 v[182:185], v149 offset:49152
	global_load_lds_dwordx4 v132, s[98:99]
	s_add_i32 m0, s28, 0x2000
	s_add_u32 s26, s26, 0x40080
	s_addc_u32 s27, s27, 0
	s_add_i32 s28, s59, s34
	global_load_lds_dwordx4 v128, s[98:99]
	s_mov_b32 m0, s28
	ds_read_b128 v[186:189], v149 offset:50176
	global_load_lds_dwordx4 v132, s[26:27]
	s_add_i32 m0, s28, 0x2000
	ds_read_b128 v[190:193], v149 offset:51200
	global_load_lds_dwordx4 v128, s[26:27]
	s_mov_b32 m0, s44
	ds_read_b128 v[194:197], v149 offset:52224
	global_load_lds_dwordx4 v134, s[100:101]
	s_mov_b32 m0, s45
	ds_read_b128 v[198:201], v149 offset:53248
	global_load_lds_dwordx4 v130, s[100:101]
	ds_read_b128 v[202:205], v149 offset:54272
	ds_read_b128 v[206:209], v149 offset:55296
	ds_read_b128 v[210:213], v149 offset:56320
	s_waitcnt vmcnt(8)
	s_waitcnt lgkmcnt(0)
	s_barrier
	s_setprio 1
	v_mfma_f32_16x16x32_bf16 v[60:63], v[150:153], v[182:185], v[60:63]
	v_mfma_f32_16x16x32_bf16 v[56:59], v[158:161], v[182:185], v[56:59]
	v_mfma_f32_16x16x32_bf16 v[44:47], v[150:153], v[190:193], v[44:47]
	v_mfma_f32_16x16x32_bf16 v[40:43], v[158:161], v[190:193], v[40:43]
	v_mfma_f32_16x16x32_bf16 v[28:31], v[150:153], v[198:201], v[28:31]
	v_mfma_f32_16x16x32_bf16 v[24:27], v[158:161], v[198:201], v[24:27]
	v_mfma_f32_16x16x32_bf16 v[12:15], v[150:153], v[206:209], v[12:15]
	v_mfma_f32_16x16x32_bf16 v[8:11], v[158:161], v[206:209], v[8:11]
	v_mfma_f32_16x16x32_bf16 v[60:63], v[154:157], v[186:189], v[60:63]
	v_mfma_f32_16x16x32_bf16 v[56:59], v[162:165], v[186:189], v[56:59]
	v_mfma_f32_16x16x32_bf16 v[44:47], v[154:157], v[194:197], v[44:47]
	v_mfma_f32_16x16x32_bf16 v[40:43], v[162:165], v[194:197], v[40:43]
	v_mfma_f32_16x16x32_bf16 v[28:31], v[154:157], v[202:205], v[28:31]
	v_mfma_f32_16x16x32_bf16 v[24:27], v[162:165], v[202:205], v[24:27]
	v_mfma_f32_16x16x32_bf16 v[12:15], v[154:157], v[210:213], v[12:15]
	v_mfma_f32_16x16x32_bf16 v[8:11], v[162:165], v[210:213], v[8:11]
	v_mfma_f32_16x16x32_bf16 v[52:55], v[166:169], v[182:185], v[52:55]
	v_mfma_f32_16x16x32_bf16 v[48:51], v[174:177], v[182:185], v[48:51]
	v_mfma_f32_16x16x32_bf16 v[36:39], v[166:169], v[190:193], v[36:39]
	v_mfma_f32_16x16x32_bf16 v[32:35], v[174:177], v[190:193], v[32:35]
	v_mfma_f32_16x16x32_bf16 v[20:23], v[166:169], v[198:201], v[20:23]
	v_mfma_f32_16x16x32_bf16 v[16:19], v[174:177], v[198:201], v[16:19]
	v_mfma_f32_16x16x32_bf16 v[4:7], v[166:169], v[206:209], v[4:7]
	v_mfma_f32_16x16x32_bf16 v[0:3], v[174:177], v[206:209], v[0:3]
	v_mfma_f32_16x16x32_bf16 v[52:55], v[170:173], v[186:189], v[52:55]
	v_mfma_f32_16x16x32_bf16 v[48:51], v[178:181], v[186:189], v[48:51]
	v_mfma_f32_16x16x32_bf16 v[36:39], v[170:173], v[194:197], v[36:39]
	v_mfma_f32_16x16x32_bf16 v[32:35], v[178:181], v[194:197], v[32:35]
	v_mfma_f32_16x16x32_bf16 v[20:23], v[170:173], v[202:205], v[20:23]
	v_mfma_f32_16x16x32_bf16 v[16:19], v[178:181], v[202:205], v[16:19]
	v_mfma_f32_16x16x32_bf16 v[4:7], v[170:173], v[210:213], v[4:7]
	v_mfma_f32_16x16x32_bf16 v[0:3], v[178:181], v[210:213], v[0:3]
	s_setprio 0
	s_barrier
	s_add_i32 s56, s56, 2
	s_add_u32 s24, s24, 0x100
	s_addc_u32 s25, s25, 0
	s_add_u32 s54, s54, 0x100
	s_addc_u32 s55, s55, 0
	s_cmp_gt_u32 s56, 13
	s_cbranch_scc0 .LBB0_376
	s_and_b64 vcc, exec, s[12:13]
	s_cbranch_vccz .LBB0_379
	s_barrier

; #define PG8_STAGE(bufoff, gbase, voff) do { _Pragma("unroll") for (int _i = 0; _i < 2; ++_i) \
;         __builtin_amdgcn_global_load_lds((const unsigned*)((const char*)(gbase) + (voff)[_i]), (PG8_LAS unsigned*)(lds + (bufoff) + ldsw + _i * 8192), 16, 0, 0); } while (0)
; #define PG8_LDA(dst, b, h) do { _Pragma("unroll") for (int m = 0; m < 4; ++m) _Pragma("unroll") for (int k = 0; k < 2; ++k) dst[m][k] = *(const PG8_LAS bf16x8*)(lds + PG8_SA(b, h) + aoff + m * 2048 + k * 1024); } while (0)
; #define PG8_LDB(dst, b, h) do { _Pragma("unroll") for (int n = 0; n < 2; ++n) _Pragma("unroll") for (int k = 0; k < 2; ++k) dst[n][k] = *(const PG8_LAS bf16x8*)(lds + PG8_SB(b, h) + boff + n * 2048 + k * 1024); } while (0)
; #define PG8_MMA(ai, bj, At, Bt) do { __builtin_amdgcn_s_setprio(1); _Pragma("unroll") for (int m = 0; m < 4; ++m) _Pragma("unroll") for (int n = 0; n < 2; ++n) _Pragma("unroll") for (int k = 0; k < 2; ++k) \
;         acc[ai][bj][m][n] = __builtin_amdgcn_mfma_f32_16x16x32_bf16(Bt[n][k], At[m][k], acc[ai][bj][m][n], 0, 0, 0); __builtin_amdgcn_s_setprio(0); } while (0)
; #define PG8_WAIT_V(n) asm volatile("s_waitcnt vmcnt(" #n ")" ::: "memory")
; #define PG8_WAIT_L(n) asm volatile("s_waitcnt lgkmcnt(" #n ")" ::: "memory")
; #define PG8_BAR __builtin_amdgcn_s_barrier()
; #define PG8_SCHED __builtin_amdgcn_sched_barrier(0)
; template <class Epi, class Sched, bool ALIGN_EPI = false, bool SP2 = false>
; __device__ __forceinline__ void gemm_phase(PG8_LAS unsigned char* lds, const Gemm g, const Sched& S, const Epi& E, int tid_in) {
;     ...
;             PG8_LDB(B0, 0, 0); PG8_LDB(B1, 0, 1); PG8_SCHED; PG8_LDA(At, 0, 0); PG8_STAGE(PG8_SA(1, 1), a1 + hstep, voffA);
;             PG8_WAIT_V(8); PG8_WAIT_L(0); PG8_BAR; PG8_MMA(0, 0, At, B0); PG8_MMA(0, 1, At, B1); PG8_BAR; PG8_SCHED;
;             PG8_LDA(At, 0, 1); PG8_STAGE(PG8_SB(0, 0), b2, voffB); PG8_STAGE(PG8_SB(0, 1), b2 + hstep, voffB); PG8_STAGE(PG8_SA(0, 0), a2, voffA);
;             PG8_WAIT_V(8); PG8_WAIT_L(0); PG8_BAR; PG8_MMA(1, 0, At, B0); PG8_MMA(1, 1, At, B1); PG8_BAR; PG8_SCHED;
.LBB0_461:
	s_add_u32 s6, s48, 0x100
	s_addc_u32 s7, s49, 0
	s_cmp_eq_u32 s76, 40
	s_cselect_b32 s53, s45, s7
	s_cselect_b32 s52, s44, s6
	s_cselect_b32 s51, s47, s75
	s_cselect_b32 s50, s46, s12
	s_add_i32 m0, s60, 0xc000
	ds_read_b128 v[128:131], v236
	global_load_lds_dwordx4 v200, s[48:49]
	s_add_i32 m0, s60, 0xe000
	ds_read_b128 v[132:135], v236 offset:1024
	global_load_lds_dwordx4 v202, s[48:49]
	ds_read_b128 v[136:139], v236 offset:2048
	ds_read_b128 v[140:143], v236 offset:3072
	ds_read_b128 v[144:147], v237
	ds_read_b128 v[148:151], v237 offset:1024
	ds_read_b128 v[152:155], v237 offset:2048
	ds_read_b128 v[156:159], v237 offset:3072
	ds_read_b128 v[160:163], v238
	ds_read_b128 v[164:167], v238 offset:1024
	ds_read_b128 v[168:171], v238 offset:2048
	ds_read_b128 v[172:175], v238 offset:3072
	ds_read_b128 v[176:179], v238 offset:4096
	ds_read_b128 v[180:183], v238 offset:5120
	ds_read_b128 v[184:187], v238 offset:6144
	ds_read_b128 v[188:191], v238 offset:7168
	s_waitcnt vmcnt(8)
	s_waitcnt lgkmcnt(0)
	s_barrier
	s_setprio 1
	v_mfma_f32_16x16x32_bf16 v[124:127], v[128:131], v[160:163], v[124:127]
	v_mfma_f32_16x16x32_bf16 v[120:123], v[136:139], v[160:163], v[120:123]
	v_mfma_f32_16x16x32_bf16 v[108:111], v[128:131], v[168:171], v[108:111]
	v_mfma_f32_16x16x32_bf16 v[104:107], v[136:139], v[168:171], v[104:107]
	v_mfma_f32_16x16x32_bf16 v[92:95], v[128:131], v[176:179], v[92:95]
	v_mfma_f32_16x16x32_bf16 v[88:91], v[136:139], v[176:179], v[88:91]
	v_mfma_f32_16x16x32_bf16 v[76:79], v[128:131], v[184:187], v[76:79]
	v_mfma_f32_16x16x32_bf16 v[72:75], v[136:139], v[184:187], v[72:75]
	v_mfma_f32_16x16x32_bf16 v[124:127], v[132:135], v[164:167], v[124:127]
	v_mfma_f32_16x16x32_bf16 v[120:123], v[140:143], v[164:167], v[120:123]
	v_mfma_f32_16x16x32_bf16 v[108:111], v[132:135], v[172:175], v[108:111]
	v_mfma_f32_16x16x32_bf16 v[104:107], v[140:143], v[172:175], v[104:107]
	v_mfma_f32_16x16x32_bf16 v[92:95], v[132:135], v[180:183], v[92:95]
	v_mfma_f32_16x16x32_bf16 v[88:91], v[140:143], v[180:183], v[88:91]
	v_mfma_f32_16x16x32_bf16 v[76:79], v[132:135], v[188:191], v[76:79]
	v_mfma_f32_16x16x32_bf16 v[72:75], v[140:143], v[188:191], v[72:75]
	v_mfma_f32_16x16x32_bf16 v[116:119], v[144:147], v[160:163], v[116:119]
	v_mfma_f32_16x16x32_bf16 v[112:115], v[152:155], v[160:163], v[112:115]
	v_mfma_f32_16x16x32_bf16 v[100:103], v[144:147], v[168:171], v[100:103]
	v_mfma_f32_16x16x32_bf16 v[96:99], v[152:155], v[168:171], v[96:99]
	v_mfma_f32_16x16x32_bf16 v[84:87], v[144:147], v[176:179], v[84:87]
	v_mfma_f32_16x16x32_bf16 v[80:83], v[152:155], v[176:179], v[80:83]
	v_mfma_f32_16x16x32_bf16 v[68:71], v[144:147], v[184:187], v[68:71]
	v_mfma_f32_16x16x32_bf16 v[64:67], v[152:155], v[184:187], v[64:67]
	v_mfma_f32_16x16x32_bf16 v[116:119], v[148:151], v[164:167], v[116:119]
	v_mfma_f32_16x16x32_bf16 v[112:115], v[156:159], v[164:167], v[112:115]
	v_mfma_f32_16x16x32_bf16 v[100:103], v[148:151], v[172:175], v[100:103]
	v_mfma_f32_16x16x32_bf16 v[96:99], v[156:159], v[172:175], v[96:99]
	v_mfma_f32_16x16x32_bf16 v[84:87], v[148:151], v[180:183], v[84:87]
	v_mfma_f32_16x16x32_bf16 v[80:83], v[156:159], v[180:183], v[80:83]
	v_mfma_f32_16x16x32_bf16 v[68:71], v[148:151], v[188:191], v[68:71]
	v_mfma_f32_16x16x32_bf16 v[64:67], v[156:159], v[188:191], v[64:67]
	s_setprio 0
	s_barrier
	s_add_u32 s98, s50, s22
	s_addc_u32 s99, s51, s23
	s_add_u32 s100, s52, s22
	s_addc_u32 s101, s53, s23
	s_add_i32 s48, s70, s59
	s_mov_b32 m0, s48
	ds_read_b128 v[160:163], v238 offset:16384
	global_load_lds_dwordx4 v194, s[50:51]
	s_add_i32 m0, s48, 0x2000
	s_add_u32 s48, s50, 0xb0000
	s_addc_u32 s49, s51, 0
	s_add_i32 s77, s71, s59
	global_load_lds_dwordx4 v198, s[50:51]
	s_mov_b32 m0, s77
	ds_read_b128 v[164:167], v238 offset:17408
	global_load_lds_dwordx4 v194, s[48:49]
	s_add_i32 m0, s77, 0x2000
	ds_read_b128 v[168:171], v238 offset:18432
	global_load_lds_dwordx4 v198, s[48:49]
	s_mov_b32 m0, s60
	ds_read_b128 v[172:175], v238 offset:19456
	global_load_lds_dwordx4 v192, s[52:53]
	s_mov_b32 m0, s61
	ds_read_b128 v[176:179], v238 offset:20480
	global_load_lds_dwordx4 v196, s[52:53]
	ds_read_b128 v[180:183], v238 offset:21504
	ds_read_b128 v[184:187], v238 offset:22528
	ds_read_b128 v[188:191], v238 offset:23552
	s_waitcnt vmcnt(8)
	s_waitcnt lgkmcnt(0)
	s_barrier
	s_setprio 1
	v_mfma_f32_16x16x32_bf16 v[60:63], v[128:131], v[160:163], v[60:63]
	v_mfma_f32_16x16x32_bf16 v[56:59], v[136:139], v[160:163], v[56:59]
	v_mfma_f32_16x16x32_bf16 v[44:47], v[128:131], v[168:171], v[44:47]
	v_mfma_f32_16x16x32_bf16 v[40:43], v[136:139], v[168:171], v[40:43]
	v_mfma_f32_16x16x32_bf16 v[28:31], v[128:131], v[176:179], v[28:31]
	v_mfma_f32_16x16x32_bf16 v[24:27], v[136:139], v[176:179], v[24:27]
	v_mfma_f32_16x16x32_bf16 v[12:15], v[128:131], v[184:187], v[12:15]
	v_mfma_f32_16x16x32_bf16 v[8:11], v[136:139], v[184:187], v[8:11]
	v_mfma_f32_16x16x32_bf16 v[60:63], v[132:135], v[164:167], v[60:63]
	v_mfma_f32_16x16x32_bf16 v[56:59], v[140:143], v[164:167], v[56:59]
	v_mfma_f32_16x16x32_bf16 v[44:47], v[132:135], v[172:175], v[44:47]
	v_mfma_f32_16x16x32_bf16 v[40:43], v[140:143], v[172:175], v[40:43]
	v_mfma_f32_16x16x32_bf16 v[28:31], v[132:135], v[180:183], v[28:31]
	v_mfma_f32_16x16x32_bf16 v[24:27], v[140:143], v[180:183], v[24:27]
	v_mfma_f32_16x16x32_bf16 v[12:15], v[132:135], v[188:191], v[12:15]
	v_mfma_f32_16x16x32_bf16 v[8:11], v[140:143], v[188:191], v[8:11]
	v_mfma_f32_16x16x32_bf16 v[52:55], v[144:147], v[160:163], v[52:55]
	v_mfma_f32_16x16x32_bf16 v[48:51], v[152:155], v[160:163], v[48:51]
	v_mfma_f32_16x16x32_bf16 v[36:39], v[144:147], v[168:171], v[36:39]
	v_mfma_f32_16x16x32_bf16 v[32:35], v[152:155], v[168:171], v[32:35]
	v_mfma_f32_16x16x32_bf16 v[20:23], v[144:147], v[176:179], v[20:23]
	v_mfma_f32_16x16x32_bf16 v[16:19], v[152:155], v[176:179], v[16:19]
	v_mfma_f32_16x16x32_bf16 v[4:7], v[144:147], v[184:187], v[4:7]
	v_mfma_f32_16x16x32_bf16 v[0:3], v[152:155], v[184:187], v[0:3]
	v_mfma_f32_16x16x32_bf16 v[52:55], v[148:151], v[164:167], v[52:55]
	v_mfma_f32_16x16x32_bf16 v[48:51], v[156:159], v[164:167], v[48:51]
	v_mfma_f32_16x16x32_bf16 v[36:39], v[148:151], v[172:175], v[36:39]
	v_mfma_f32_16x16x32_bf16 v[32:35], v[156:159], v[172:175], v[32:35]
	v_mfma_f32_16x16x32_bf16 v[20:23], v[148:151], v[180:183], v[20:23]
	v_mfma_f32_16x16x32_bf16 v[16:19], v[156:159], v[180:183], v[16:19]
	v_mfma_f32_16x16x32_bf16 v[4:7], v[148:151], v[188:191], v[4:7]
	v_mfma_f32_16x16x32_bf16 v[0:3], v[156:159], v[188:191], v[0:3]
	s_setprio 0
	s_barrier
; #define PG8_STAGE(bufoff, gbase, voff) do { _Pragma("unroll") for (int _i = 0; _i < 2; ++_i) \
;         __builtin_amdgcn_global_load_lds((const unsigned*)((const char*)(gbase) + (voff)[_i]), (PG8_LAS unsigned*)(lds + (bufoff) + ldsw + _i * 8192), 16, 0, 0); } while (0)
; #define PG8_LDA(dst, b, h) do { _Pragma("unroll") for (int m = 0; m < 4; ++m) _Pragma("unroll") for (int k = 0; k < 2; ++k) dst[m][k] = *(const PG8_LAS bf16x8*)(lds + PG8_SA(b, h) + aoff + m * 2048 + k * 1024); } while (0)
; #define PG8_LDB(dst, b, h) do { _Pragma("unroll") for (int n = 0; n < 2; ++n) _Pragma("unroll") for (int k = 0; k < 2; ++k) dst[n][k] = *(const PG8_LAS bf16x8*)(lds + PG8_SB(b, h) + boff + n * 2048 + k * 1024); } while (0)
; #define PG8_MMA(ai, bj, At, Bt) do { __builtin_amdgcn_s_setprio(1); _Pragma("unroll") for (int m = 0; m < 4; ++m) _Pragma("unroll") for (int n = 0; n < 2; ++n) _Pragma("unroll") for (int k = 0; k < 2; ++k) \
;         acc[ai][bj][m][n] = __builtin_amdgcn_mfma_f32_16x16x32_bf16(Bt[n][k], At[m][k], acc[ai][bj][m][n], 0, 0, 0); __builtin_amdgcn_s_setprio(0); } while (0)
; #define PG8_WAIT_V(n) asm volatile("s_waitcnt vmcnt(" #n ")" ::: "memory")
; #define PG8_WAIT_L(n) asm volatile("s_waitcnt lgkmcnt(" #n ")" ::: "memory")
; #define PG8_BAR __builtin_amdgcn_s_barrier()
; #define PG8_SCHED __builtin_amdgcn_sched_barrier(0)
; template <class Epi, class Sched, bool ALIGN_EPI = false, bool SP2 = false>
; __device__ __forceinline__ void gemm_phase(PG8_LAS unsigned char* lds, const Gemm g, const Sched& S, const Epi& E, int tid_in) {
;     ...
;             PG8_LDB(B0, 1, 0); PG8_LDB(B1, 1, 1); PG8_SCHED; PG8_LDA(At, 1, 0); PG8_STAGE(PG8_SA(0, 1), a2 + hstep, voffA);
;             PG8_WAIT_V(8); PG8_WAIT_L(0); PG8_BAR; PG8_MMA(0, 0, At, B0); PG8_MMA(0, 1, At, B1); PG8_BAR; PG8_SCHED;
;             PG8_LDA(At, 1, 1); PG8_STAGE(PG8_SB(1, 0), b3, voffB); PG8_STAGE(PG8_SB(1, 1), b3 + hstep, voffB); PG8_STAGE(PG8_SA(1, 0), a3, voffA);
;             PG8_WAIT_V(8); PG8_WAIT_L(0); PG8_BAR; PG8_MMA(1, 0, At, B0); PG8_MMA(1, 1, At, B1); PG8_BAR; PG8_SCHED;
	s_add_i32 s77, 0, 0x18000
	s_add_i32 s78, 0, 0x1c000
	s_add_u32 s48, s52, 0xb0000
	s_addc_u32 s49, s53, 0
	s_mov_b32 m0, s62
	s_nop 0
	global_load_lds_dwordx4 v192, s[48:49]
	s_mov_b32 m0, s63
	s_nop 0
	global_load_lds_dwordx4 v196, s[48:49]
	v_add_u32_e32 v140, s77, v232
	v_add_u32_e32 v156, s78, v232
	ds_read_b128 v[128:131], v140
	ds_read_b128 v[132:135], v140 offset:1024
	ds_read_b128 v[136:139], v140 offset:2048
	ds_read_b128 v[140:143], v140 offset:3072
	ds_read_b128 v[144:147], v156
	ds_read_b128 v[148:151], v156 offset:1024
	ds_read_b128 v[152:155], v156 offset:2048
	ds_read_b128 v[156:159], v156 offset:3072
	ds_read_b128 v[160:163], v238 offset:32768
	ds_read_b128 v[164:167], v238 offset:33792
	ds_read_b128 v[168:171], v238 offset:34816
	ds_read_b128 v[172:175], v238 offset:35840
	ds_read_b128 v[176:179], v238 offset:36864
	ds_read_b128 v[180:183], v238 offset:37888
	ds_read_b128 v[184:187], v238 offset:38912
	ds_read_b128 v[188:191], v238 offset:39936
	s_waitcnt vmcnt(8)
	s_waitcnt lgkmcnt(0)
	s_barrier
	s_setprio 1
	v_mfma_f32_16x16x32_bf16 v[124:127], v[128:131], v[160:163], v[124:127]
	v_mfma_f32_16x16x32_bf16 v[120:123], v[136:139], v[160:163], v[120:123]
	v_mfma_f32_16x16x32_bf16 v[108:111], v[128:131], v[168:171], v[108:111]
	v_mfma_f32_16x16x32_bf16 v[104:107], v[136:139], v[168:171], v[104:107]
	v_mfma_f32_16x16x32_bf16 v[92:95], v[128:131], v[176:179], v[92:95]
	v_mfma_f32_16x16x32_bf16 v[88:91], v[136:139], v[176:179], v[88:91]
	v_mfma_f32_16x16x32_bf16 v[76:79], v[128:131], v[184:187], v[76:79]
	v_mfma_f32_16x16x32_bf16 v[72:75], v[136:139], v[184:187], v[72:75]
	v_mfma_f32_16x16x32_bf16 v[124:127], v[132:135], v[164:167], v[124:127]
	v_mfma_f32_16x16x32_bf16 v[120:123], v[140:143], v[164:167], v[120:123]
	v_mfma_f32_16x16x32_bf16 v[108:111], v[132:135], v[172:175], v[108:111]
	v_mfma_f32_16x16x32_bf16 v[104:107], v[140:143], v[172:175], v[104:107]
	v_mfma_f32_16x16x32_bf16 v[92:95], v[132:135], v[180:183], v[92:95]
	v_mfma_f32_16x16x32_bf16 v[88:91], v[140:143], v[180:183], v[88:91]
	v_mfma_f32_16x16x32_bf16 v[76:79], v[132:135], v[188:191], v[76:79]
	v_mfma_f32_16x16x32_bf16 v[72:75], v[140:143], v[188:191], v[72:75]
	v_mfma_f32_16x16x32_bf16 v[116:119], v[144:147], v[160:163], v[116:119]
	v_mfma_f32_16x16x32_bf16 v[112:115], v[152:155], v[160:163], v[112:115]
	v_mfma_f32_16x16x32_bf16 v[100:103], v[144:147], v[168:171], v[100:103]
	v_mfma_f32_16x16x32_bf16 v[96:99], v[152:155], v[168:171], v[96:99]
	v_mfma_f32_16x16x32_bf16 v[84:87], v[144:147], v[176:179], v[84:87]
	v_mfma_f32_16x16x32_bf16 v[80:83], v[152:155], v[176:179], v[80:83]
	v_mfma_f32_16x16x32_bf16 v[68:71], v[144:147], v[184:187], v[68:71]
	v_mfma_f32_16x16x32_bf16 v[64:67], v[152:155], v[184:187], v[64:67]
	v_mfma_f32_16x16x32_bf16 v[116:119], v[148:151], v[164:167], v[116:119]
	v_mfma_f32_16x16x32_bf16 v[112:115], v[156:159], v[164:167], v[112:115]
	v_mfma_f32_16x16x32_bf16 v[100:103], v[148:151], v[172:175], v[100:103]
	v_mfma_f32_16x16x32_bf16 v[96:99], v[156:159], v[172:175], v[96:99]
	v_mfma_f32_16x16x32_bf16 v[84:87], v[148:151], v[180:183], v[84:87]
	v_mfma_f32_16x16x32_bf16 v[80:83], v[156:159], v[180:183], v[80:83]
	v_mfma_f32_16x16x32_bf16 v[68:71], v[148:151], v[188:191], v[68:71]
	v_mfma_f32_16x16x32_bf16 v[64:67], v[156:159], v[188:191], v[64:67]
	s_setprio 0
	s_barrier
	s_add_i32 s48, s77, s59
	s_mov_b32 m0, s48
	ds_read_b128 v[160:163], v238 offset:49152
	global_load_lds_dwordx4 v194, s[98:99]
	s_add_i32 m0, s48, 0x2000
	s_add_u32 s48, s50, 0xb0080
	s_addc_u32 s49, s51, 0
	s_add_i32 s50, s78, s59
	global_load_lds_dwordx4 v198, s[98:99]
	s_mov_b32 m0, s50
	ds_read_b128 v[164:167], v238 offset:50176
	global_load_lds_dwordx4 v194, s[48:49]
	s_add_i32 m0, s50, 0x2000
	ds_read_b128 v[168:171], v238 offset:51200
	global_load_lds_dwordx4 v198, s[48:49]
	s_mov_b32 m0, s65
	ds_read_b128 v[172:175], v238 offset:52224
	global_load_lds_dwordx4 v192, s[100:101]
	s_mov_b32 m0, s67
	ds_read_b128 v[176:179], v238 offset:53248
	global_load_lds_dwordx4 v196, s[100:101]
	ds_read_b128 v[180:183], v238 offset:54272
	ds_read_b128 v[184:187], v238 offset:55296
	ds_read_b128 v[188:191], v238 offset:56320
	s_waitcnt vmcnt(8)
	s_waitcnt lgkmcnt(0)
	s_barrier
	s_setprio 1
	v_mfma_f32_16x16x32_bf16 v[60:63], v[128:131], v[160:163], v[60:63]
	v_mfma_f32_16x16x32_bf16 v[56:59], v[136:139], v[160:163], v[56:59]
	v_mfma_f32_16x16x32_bf16 v[44:47], v[128:131], v[168:171], v[44:47]
	v_mfma_f32_16x16x32_bf16 v[40:43], v[136:139], v[168:171], v[40:43]
	v_mfma_f32_16x16x32_bf16 v[28:31], v[128:131], v[176:179], v[28:31]
	v_mfma_f32_16x16x32_bf16 v[24:27], v[136:139], v[176:179], v[24:27]
	v_mfma_f32_16x16x32_bf16 v[12:15], v[128:131], v[184:187], v[12:15]
	v_mfma_f32_16x16x32_bf16 v[8:11], v[136:139], v[184:187], v[8:11]
	v_mfma_f32_16x16x32_bf16 v[60:63], v[132:135], v[164:167], v[60:63]
	v_mfma_f32_16x16x32_bf16 v[56:59], v[140:143], v[164:167], v[56:59]
	v_mfma_f32_16x16x32_bf16 v[44:47], v[132:135], v[172:175], v[44:47]
	v_mfma_f32_16x16x32_bf16 v[40:43], v[140:143], v[172:175], v[40:43]
	v_mfma_f32_16x16x32_bf16 v[28:31], v[132:135], v[180:183], v[28:31]
	v_mfma_f32_16x16x32_bf16 v[24:27], v[140:143], v[180:183], v[24:27]
	v_mfma_f32_16x16x32_bf16 v[12:15], v[132:135], v[188:191], v[12:15]
	v_mfma_f32_16x16x32_bf16 v[8:11], v[140:143], v[188:191], v[8:11]
	v_mfma_f32_16x16x32_bf16 v[52:55], v[144:147], v[160:163], v[52:55]
	v_mfma_f32_16x16x32_bf16 v[48:51], v[152:155], v[160:163], v[48:51]
	v_mfma_f32_16x16x32_bf16 v[36:39], v[144:147], v[168:171], v[36:39]
	v_mfma_f32_16x16x32_bf16 v[32:35], v[152:155], v[168:171], v[32:35]
	v_mfma_f32_16x16x32_bf16 v[20:23], v[144:147], v[176:179], v[20:23]
	v_mfma_f32_16x16x32_bf16 v[16:19], v[152:155], v[176:179], v[16:19]
	v_mfma_f32_16x16x32_bf16 v[4:7], v[144:147], v[184:187], v[4:7]
	v_mfma_f32_16x16x32_bf16 v[0:3], v[152:155], v[184:187], v[0:3]
	v_mfma_f32_16x16x32_bf16 v[52:55], v[148:151], v[164:167], v[52:55]
	v_mfma_f32_16x16x32_bf16 v[48:51], v[156:159], v[164:167], v[48:51]
	v_mfma_f32_16x16x32_bf16 v[36:39], v[148:151], v[172:175], v[36:39]
	v_mfma_f32_16x16x32_bf16 v[32:35], v[156:159], v[172:175], v[32:35]
	v_mfma_f32_16x16x32_bf16 v[20:23], v[148:151], v[180:183], v[20:23]
	v_mfma_f32_16x16x32_bf16 v[16:19], v[156:159], v[180:183], v[16:19]
	v_mfma_f32_16x16x32_bf16 v[4:7], v[148:151], v[188:191], v[4:7]
	v_mfma_f32_16x16x32_bf16 v[0:3], v[156:159], v[188:191], v[0:3]
	s_setprio 0
	s_barrier
	s_add_i32 s76, s76, 2
	s_add_u32 s12, s12, 0x100
	s_addc_u32 s75, s75, 0
	s_cmp_gt_u32 s76, 41
	s_mov_b64 s[48:49], s[6:7]
	s_cbranch_scc0 .LBB0_461
	s_and_b64 vcc, exec, s[24:25]
	s_cbranch_vccz .LBB0_464
	s_barrier

; #define PG8_STAGE(bufoff, gbase, voff) do { _Pragma("unroll") for (int _i = 0; _i < 2; ++_i) \
;         __builtin_amdgcn_global_load_lds((const unsigned*)((const char*)(gbase) + (voff)[_i]), (PG8_LAS unsigned*)(lds + (bufoff) + ldsw + _i * 8192), 16, 0, 0); } while (0)
; #define PG8_LDA(dst, b, h) do { _Pragma("unroll") for (int m = 0; m < 4; ++m) _Pragma("unroll") for (int k = 0; k < 2; ++k) dst[m][k] = *(const PG8_LAS bf16x8*)(lds + PG8_SA(b, h) + aoff + m * 2048 + k * 1024); } while (0)
; #define PG8_LDB(dst, b, h) do { _Pragma("unroll") for (int n = 0; n < 2; ++n) _Pragma("unroll") for (int k = 0; k < 2; ++k) dst[n][k] = *(const PG8_LAS bf16x8*)(lds + PG8_SB(b, h) + boff + n * 2048 + k * 1024); } while (0)
; #define PG8_MMA(ai, bj, At, Bt) do { __builtin_amdgcn_s_setprio(1); _Pragma("unroll") for (int m = 0; m < 4; ++m) _Pragma("unroll") for (int n = 0; n < 2; ++n) _Pragma("unroll") for (int k = 0; k < 2; ++k) \
;         acc[ai][bj][m][n] = __builtin_amdgcn_mfma_f32_16x16x32_bf16(Bt[n][k], At[m][k], acc[ai][bj][m][n], 0, 0, 0); __builtin_amdgcn_s_setprio(0); } while (0)
; #define PG8_WAIT_V(n) asm volatile("s_waitcnt vmcnt(" #n ")" ::: "memory")
; #define PG8_WAIT_L(n) asm volatile("s_waitcnt lgkmcnt(" #n ")" ::: "memory")
; #define PG8_BAR __builtin_amdgcn_s_barrier()
; #define PG8_SCHED __builtin_amdgcn_sched_barrier(0)
; template <class Epi, class Sched, bool ALIGN_EPI = false, bool SP2 = false>
; __device__ __forceinline__ void gemm_phase(PG8_LAS unsigned char* lds, const Gemm g, const Sched& S, const Epi& E, int tid_in) {
;     ...
;             PG8_LDB(B0, 0, 0); PG8_LDB(B1, 0, 1); PG8_SCHED; PG8_LDA(At, 0, 0); PG8_STAGE(PG8_SA(1, 1), a1 + hstep, voffA);
;             PG8_WAIT_V(8); PG8_WAIT_L(0); PG8_BAR; PG8_MMA(0, 0, At, B0); PG8_MMA(0, 1, At, B1); PG8_BAR; PG8_SCHED;
;             PG8_LDA(At, 0, 1); PG8_STAGE(PG8_SB(0, 0), b2, voffB); PG8_STAGE(PG8_SB(0, 1), b2 + hstep, voffB); PG8_STAGE(PG8_SA(0, 0), a2, voffA);
;             PG8_WAIT_V(8); PG8_WAIT_L(0); PG8_BAR; PG8_MMA(1, 0, At, B0); PG8_MMA(1, 1, At, B1); PG8_BAR; PG8_SCHED;
.LBB0_564:
	s_add_u32 s48, s46, 0xfffc0080
	s_addc_u32 s49, s47, -1
	s_cmp_eq_u32 s52, 12
	s_cselect_b32 s51, s0, s49
	s_cselect_b32 s50, s1, s48
	s_cselect_b32 s49, s7, s45
	s_cselect_b32 s48, s31, s35
	s_add_i32 m0, s59, 0xc000
	ds_read_b128 v[128:131], v180
	global_load_lds_dwordx4 v158, s[46:47]
	s_add_i32 m0, s59, 0xe000
	ds_read_b128 v[132:135], v180 offset:1024
	global_load_lds_dwordx4 v160, s[46:47]
	ds_read_b128 v[136:139], v180 offset:2048
	ds_read_b128 v[140:143], v180 offset:3072
	ds_read_b128 v[166:169], v181
	ds_read_b128 v[170:173], v181 offset:1024
	ds_read_b128 v[174:177], v181 offset:2048
	ds_read_b128 v[184:187], v181 offset:3072
	ds_read_b128 v[188:191], v182
	ds_read_b128 v[192:195], v182 offset:1024
	ds_read_b128 v[196:199], v182 offset:2048
	ds_read_b128 v[200:203], v182 offset:3072
	ds_read_b128 v[204:207], v182 offset:4096
	ds_read_b128 v[208:211], v182 offset:5120
	ds_read_b128 v[212:215], v182 offset:6144
	ds_read_b128 v[216:219], v182 offset:7168
	s_waitcnt vmcnt(8)
	s_waitcnt lgkmcnt(0)
	s_barrier
	s_setprio 1
	v_mfma_f32_16x16x32_bf16 v[68:71], v[128:131], v[188:191], v[68:71]
	v_mfma_f32_16x16x32_bf16 v[56:59], v[136:139], v[188:191], v[56:59]
	v_mfma_f32_16x16x32_bf16 v[52:55], v[128:131], v[196:199], v[52:55]
	v_mfma_f32_16x16x32_bf16 v[48:51], v[136:139], v[196:199], v[48:51]
	v_mfma_f32_16x16x32_bf16 v[44:47], v[128:131], v[204:207], v[44:47]
	v_mfma_f32_16x16x32_bf16 v[40:43], v[136:139], v[204:207], v[40:43]
	v_mfma_f32_16x16x32_bf16 v[36:39], v[128:131], v[212:215], v[36:39]
	v_mfma_f32_16x16x32_bf16 v[32:35], v[136:139], v[212:215], v[32:35]
	v_mfma_f32_16x16x32_bf16 v[68:71], v[132:135], v[192:195], v[68:71]
	v_mfma_f32_16x16x32_bf16 v[56:59], v[140:143], v[192:195], v[56:59]
	v_mfma_f32_16x16x32_bf16 v[52:55], v[132:135], v[200:203], v[52:55]
	v_mfma_f32_16x16x32_bf16 v[48:51], v[140:143], v[200:203], v[48:51]
	v_mfma_f32_16x16x32_bf16 v[44:47], v[132:135], v[208:211], v[44:47]
	v_mfma_f32_16x16x32_bf16 v[40:43], v[140:143], v[208:211], v[40:43]
	v_mfma_f32_16x16x32_bf16 v[36:39], v[132:135], v[216:219], v[36:39]
	v_mfma_f32_16x16x32_bf16 v[32:35], v[140:143], v[216:219], v[32:35]
	v_mfma_f32_16x16x32_bf16 v[124:127], v[166:169], v[188:191], v[124:127]
	v_mfma_f32_16x16x32_bf16 v[120:123], v[174:177], v[188:191], v[120:123]
	v_mfma_f32_16x16x32_bf16 v[116:119], v[166:169], v[196:199], v[116:119]
	v_mfma_f32_16x16x32_bf16 v[112:115], v[174:177], v[196:199], v[112:115]
	v_mfma_f32_16x16x32_bf16 v[108:111], v[166:169], v[204:207], v[108:111]
	v_mfma_f32_16x16x32_bf16 v[104:107], v[174:177], v[204:207], v[104:107]
	v_mfma_f32_16x16x32_bf16 v[100:103], v[166:169], v[212:215], v[100:103]
	v_mfma_f32_16x16x32_bf16 v[96:99], v[174:177], v[212:215], v[96:99]
	v_mfma_f32_16x16x32_bf16 v[124:127], v[170:173], v[192:195], v[124:127]
	v_mfma_f32_16x16x32_bf16 v[120:123], v[184:187], v[192:195], v[120:123]
	v_mfma_f32_16x16x32_bf16 v[116:119], v[170:173], v[200:203], v[116:119]
	v_mfma_f32_16x16x32_bf16 v[112:115], v[184:187], v[200:203], v[112:115]
	v_mfma_f32_16x16x32_bf16 v[108:111], v[170:173], v[208:211], v[108:111]
	v_mfma_f32_16x16x32_bf16 v[104:107], v[184:187], v[208:211], v[104:107]
	v_mfma_f32_16x16x32_bf16 v[100:103], v[170:173], v[216:219], v[100:103]
	v_mfma_f32_16x16x32_bf16 v[96:99], v[184:187], v[216:219], v[96:99]
	s_setprio 0
	s_barrier
	s_add_u32 s98, s48, s14
	s_addc_u32 s99, s49, s15
	s_add_u32 s100, s50, s14
	s_addc_u32 s101, s51, s15
	s_add_i32 s53, s77, s29
	s_mov_b32 m0, s53
	ds_read_b128 v[188:191], v182 offset:16384
	global_load_lds_dwordx4 v146, s[48:49]
	s_add_i32 m0, s53, 0x2000
	s_add_u32 s88, s48, 0x40000
	s_addc_u32 s89, s49, 0
	s_add_i32 s53, s78, s29
	global_load_lds_dwordx4 v150, s[48:49]
	s_mov_b32 m0, s53
	ds_read_b128 v[192:195], v182 offset:17408
	global_load_lds_dwordx4 v146, s[88:89]
	s_add_i32 m0, s53, 0x2000
	ds_read_b128 v[196:199], v182 offset:18432
	global_load_lds_dwordx4 v150, s[88:89]
	s_mov_b32 m0, s59
	ds_read_b128 v[200:203], v182 offset:19456
	global_load_lds_dwordx4 v144, s[50:51]
	s_mov_b32 m0, s60
	ds_read_b128 v[204:207], v182 offset:20480
	global_load_lds_dwordx4 v148, s[50:51]
	ds_read_b128 v[208:211], v182 offset:21504
	ds_read_b128 v[212:215], v182 offset:22528
	ds_read_b128 v[216:219], v182 offset:23552
	s_waitcnt vmcnt(8)
	s_waitcnt lgkmcnt(0)
	s_barrier
	s_setprio 1
	v_mfma_f32_16x16x32_bf16 v[28:31], v[128:131], v[188:191], v[28:31]
	v_mfma_f32_16x16x32_bf16 v[24:27], v[136:139], v[188:191], v[24:27]
	v_mfma_f32_16x16x32_bf16 v[20:23], v[128:131], v[196:199], v[20:23]
	v_mfma_f32_16x16x32_bf16 v[16:19], v[136:139], v[196:199], v[16:19]
	v_mfma_f32_16x16x32_bf16 v[12:15], v[128:131], v[204:207], v[12:15]
	v_mfma_f32_16x16x32_bf16 v[8:11], v[136:139], v[204:207], v[8:11]
	v_mfma_f32_16x16x32_bf16 v[4:7], v[128:131], v[212:215], v[4:7]
	v_mfma_f32_16x16x32_bf16 v[0:3], v[136:139], v[212:215], v[0:3]
	v_mfma_f32_16x16x32_bf16 v[28:31], v[132:135], v[192:195], v[28:31]
	v_mfma_f32_16x16x32_bf16 v[24:27], v[140:143], v[192:195], v[24:27]
	v_mfma_f32_16x16x32_bf16 v[20:23], v[132:135], v[200:203], v[20:23]
	v_mfma_f32_16x16x32_bf16 v[16:19], v[140:143], v[200:203], v[16:19]
	v_mfma_f32_16x16x32_bf16 v[12:15], v[132:135], v[208:211], v[12:15]
	v_mfma_f32_16x16x32_bf16 v[8:11], v[140:143], v[208:211], v[8:11]
	v_mfma_f32_16x16x32_bf16 v[4:7], v[132:135], v[216:219], v[4:7]
	v_mfma_f32_16x16x32_bf16 v[0:3], v[140:143], v[216:219], v[0:3]
	v_mfma_f32_16x16x32_bf16 v[92:95], v[166:169], v[188:191], v[92:95]
	v_mfma_f32_16x16x32_bf16 v[88:91], v[174:177], v[188:191], v[88:91]
	v_mfma_f32_16x16x32_bf16 v[84:87], v[166:169], v[196:199], v[84:87]
	v_mfma_f32_16x16x32_bf16 v[80:83], v[174:177], v[196:199], v[80:83]
	v_mfma_f32_16x16x32_bf16 v[76:79], v[166:169], v[204:207], v[76:79]
	v_mfma_f32_16x16x32_bf16 v[72:75], v[174:177], v[204:207], v[72:75]
	v_mfma_f32_16x16x32_bf16 v[64:67], v[166:169], v[212:215], v[64:67]
	v_mfma_f32_16x16x32_bf16 v[60:63], v[174:177], v[212:215], v[60:63]
	v_mfma_f32_16x16x32_bf16 v[92:95], v[170:173], v[192:195], v[92:95]
	v_mfma_f32_16x16x32_bf16 v[88:91], v[184:187], v[192:195], v[88:91]
	v_mfma_f32_16x16x32_bf16 v[84:87], v[170:173], v[200:203], v[84:87]
	v_mfma_f32_16x16x32_bf16 v[80:83], v[184:187], v[200:203], v[80:83]
	v_mfma_f32_16x16x32_bf16 v[76:79], v[170:173], v[208:211], v[76:79]
	v_mfma_f32_16x16x32_bf16 v[72:75], v[184:187], v[208:211], v[72:75]
	v_mfma_f32_16x16x32_bf16 v[64:67], v[170:173], v[216:219], v[64:67]
	v_mfma_f32_16x16x32_bf16 v[60:63], v[184:187], v[216:219], v[60:63]
	s_setprio 0
	s_barrier
; #define PG8_STAGE(bufoff, gbase, voff) do { _Pragma("unroll") for (int _i = 0; _i < 2; ++_i) \
;         __builtin_amdgcn_global_load_lds((const unsigned*)((const char*)(gbase) + (voff)[_i]), (PG8_LAS unsigned*)(lds + (bufoff) + ldsw + _i * 8192), 16, 0, 0); } while (0)
; #define PG8_LDA(dst, b, h) do { _Pragma("unroll") for (int m = 0; m < 4; ++m) _Pragma("unroll") for (int k = 0; k < 2; ++k) dst[m][k] = *(const PG8_LAS bf16x8*)(lds + PG8_SA(b, h) + aoff + m * 2048 + k * 1024); } while (0)
; #define PG8_LDB(dst, b, h) do { _Pragma("unroll") for (int n = 0; n < 2; ++n) _Pragma("unroll") for (int k = 0; k < 2; ++k) dst[n][k] = *(const PG8_LAS bf16x8*)(lds + PG8_SB(b, h) + boff + n * 2048 + k * 1024); } while (0)
; #define PG8_MMA(ai, bj, At, Bt) do { __builtin_amdgcn_s_setprio(1); _Pragma("unroll") for (int m = 0; m < 4; ++m) _Pragma("unroll") for (int n = 0; n < 2; ++n) _Pragma("unroll") for (int k = 0; k < 2; ++k) \
;         acc[ai][bj][m][n] = __builtin_amdgcn_mfma_f32_16x16x32_bf16(Bt[n][k], At[m][k], acc[ai][bj][m][n], 0, 0, 0); __builtin_amdgcn_s_setprio(0); } while (0)
; #define PG8_WAIT_V(n) asm volatile("s_waitcnt vmcnt(" #n ")" ::: "memory")
; #define PG8_WAIT_L(n) asm volatile("s_waitcnt lgkmcnt(" #n ")" ::: "memory")
; #define PG8_BAR __builtin_amdgcn_s_barrier()
; #define PG8_SCHED __builtin_amdgcn_sched_barrier(0)
;     __device__ __forceinline__ void operator()(const f32x4 (&acc)[2][2][4][2], const Unit& u, int wr, int wc, int fr, int fq) const {
;         const int row0 = u.pm * BM + wr * 64 + fr; const int pn = u.pn;
;         if (pn == 19) {
; template <class Epi, class Sched, bool ALIGN_EPI = false, bool SP2 = false>
; __device__ __forceinline__ void gemm_phase(PG8_LAS unsigned char* lds, const Gemm g, const Sched& S, const Epi& E, int tid_in) {
;     ...
;             PG8_LDB(B0, 1, 0); PG8_LDB(B1, 1, 1); PG8_SCHED; PG8_LDA(At, 1, 0); PG8_STAGE(PG8_SA(0, 1), a2 + hstep, voffA);
;             PG8_WAIT_V(8); PG8_WAIT_L(0); PG8_BAR; PG8_MMA(0, 0, At, B0); PG8_MMA(0, 1, At, B1); PG8_BAR; PG8_SCHED;
;             PG8_LDA(At, 1, 1); PG8_STAGE(PG8_SB(1, 0), b3, voffB); PG8_STAGE(PG8_SB(1, 1), b3 + hstep, voffB); PG8_STAGE(PG8_SA(1, 0), a3, voffA);
;             PG8_WAIT_V(8); PG8_WAIT_L(0); PG8_BAR; PG8_MMA(1, 0, At, B0); PG8_MMA(1, 1, At, B1); PG8_BAR; PG8_SCHED;
	s_add_i32 s53, 0, 0x18000
	s_add_i32 s88, 0, 0x1c000
	s_add_u32 s50, s50, 0x40000
	s_addc_u32 s51, s51, 0
	s_mov_b32 m0, s61
	s_nop 0
	global_load_lds_dwordx4 v144, s[50:51]
	s_mov_b32 m0, s62
	s_nop 0
	global_load_lds_dwordx4 v148, s[50:51]
	v_add_u32_e32 v140, s53, v179
	v_add_u32_e32 v184, s88, v179
	ds_read_b128 v[128:131], v140
	ds_read_b128 v[132:135], v140 offset:1024
	ds_read_b128 v[136:139], v140 offset:2048
	ds_read_b128 v[140:143], v140 offset:3072
	ds_read_b128 v[166:169], v184
	ds_read_b128 v[170:173], v184 offset:1024
	ds_read_b128 v[174:177], v184 offset:2048
	ds_read_b128 v[184:187], v184 offset:3072
	ds_read_b128 v[188:191], v182 offset:32768
	ds_read_b128 v[192:195], v182 offset:33792
	ds_read_b128 v[196:199], v182 offset:34816
	ds_read_b128 v[200:203], v182 offset:35840
	ds_read_b128 v[204:207], v182 offset:36864
	ds_read_b128 v[208:211], v182 offset:37888
	ds_read_b128 v[212:215], v182 offset:38912
	ds_read_b128 v[216:219], v182 offset:39936
	s_waitcnt vmcnt(8)
	s_waitcnt lgkmcnt(0)
	s_barrier
	s_setprio 1
	v_mfma_f32_16x16x32_bf16 v[68:71], v[128:131], v[188:191], v[68:71]
	v_mfma_f32_16x16x32_bf16 v[56:59], v[136:139], v[188:191], v[56:59]
	v_mfma_f32_16x16x32_bf16 v[52:55], v[128:131], v[196:199], v[52:55]
	v_mfma_f32_16x16x32_bf16 v[48:51], v[136:139], v[196:199], v[48:51]
	v_mfma_f32_16x16x32_bf16 v[44:47], v[128:131], v[204:207], v[44:47]
	v_mfma_f32_16x16x32_bf16 v[40:43], v[136:139], v[204:207], v[40:43]
	v_mfma_f32_16x16x32_bf16 v[36:39], v[128:131], v[212:215], v[36:39]
	v_mfma_f32_16x16x32_bf16 v[32:35], v[136:139], v[212:215], v[32:35]
	v_mfma_f32_16x16x32_bf16 v[68:71], v[132:135], v[192:195], v[68:71]
	v_mfma_f32_16x16x32_bf16 v[56:59], v[140:143], v[192:195], v[56:59]
	v_mfma_f32_16x16x32_bf16 v[52:55], v[132:135], v[200:203], v[52:55]
	v_mfma_f32_16x16x32_bf16 v[48:51], v[140:143], v[200:203], v[48:51]
	v_mfma_f32_16x16x32_bf16 v[44:47], v[132:135], v[208:211], v[44:47]
	v_mfma_f32_16x16x32_bf16 v[40:43], v[140:143], v[208:211], v[40:43]
	v_mfma_f32_16x16x32_bf16 v[36:39], v[132:135], v[216:219], v[36:39]
	v_mfma_f32_16x16x32_bf16 v[32:35], v[140:143], v[216:219], v[32:35]
	v_mfma_f32_16x16x32_bf16 v[124:127], v[166:169], v[188:191], v[124:127]
	v_mfma_f32_16x16x32_bf16 v[120:123], v[174:177], v[188:191], v[120:123]
	v_mfma_f32_16x16x32_bf16 v[116:119], v[166:169], v[196:199], v[116:119]
	v_mfma_f32_16x16x32_bf16 v[112:115], v[174:177], v[196:199], v[112:115]
	v_mfma_f32_16x16x32_bf16 v[108:111], v[166:169], v[204:207], v[108:111]
	v_mfma_f32_16x16x32_bf16 v[104:107], v[174:177], v[204:207], v[104:107]
	v_mfma_f32_16x16x32_bf16 v[100:103], v[166:169], v[212:215], v[100:103]
	v_mfma_f32_16x16x32_bf16 v[96:99], v[174:177], v[212:215], v[96:99]
	v_mfma_f32_16x16x32_bf16 v[124:127], v[170:173], v[192:195], v[124:127]
	v_mfma_f32_16x16x32_bf16 v[120:123], v[184:187], v[192:195], v[120:123]
	v_mfma_f32_16x16x32_bf16 v[116:119], v[170:173], v[200:203], v[116:119]
	v_mfma_f32_16x16x32_bf16 v[112:115], v[184:187], v[200:203], v[112:115]
	v_mfma_f32_16x16x32_bf16 v[108:111], v[170:173], v[208:211], v[108:111]
	v_mfma_f32_16x16x32_bf16 v[104:107], v[184:187], v[208:211], v[104:107]
	v_mfma_f32_16x16x32_bf16 v[100:103], v[170:173], v[216:219], v[100:103]
	v_mfma_f32_16x16x32_bf16 v[96:99], v[184:187], v[216:219], v[96:99]
	s_setprio 0
	s_barrier
	s_add_i32 s50, s53, s29
	s_mov_b32 m0, s50
	ds_read_b128 v[188:191], v182 offset:49152
	global_load_lds_dwordx4 v146, s[98:99]
	s_add_i32 m0, s50, 0x2000
	s_add_u32 s48, s48, 0x40080
	s_addc_u32 s49, s49, 0
	s_add_i32 s50, s88, s29
	global_load_lds_dwordx4 v150, s[98:99]
	s_mov_b32 m0, s50
	ds_read_b128 v[192:195], v182 offset:50176
	global_load_lds_dwordx4 v146, s[48:49]
	s_add_i32 m0, s50, 0x2000
	ds_read_b128 v[196:199], v182 offset:51200
	global_load_lds_dwordx4 v150, s[48:49]
	s_mov_b32 m0, s63
	ds_read_b128 v[200:203], v182 offset:52224
	global_load_lds_dwordx4 v144, s[100:101]
	s_mov_b32 m0, s64
	ds_read_b128 v[204:207], v182 offset:53248
	global_load_lds_dwordx4 v148, s[100:101]
	ds_read_b128 v[208:211], v182 offset:54272
	ds_read_b128 v[212:215], v182 offset:55296
	ds_read_b128 v[216:219], v182 offset:56320
	s_waitcnt vmcnt(8)
	s_waitcnt lgkmcnt(0)
	s_barrier
	s_setprio 1
	v_mfma_f32_16x16x32_bf16 v[28:31], v[128:131], v[188:191], v[28:31]
	v_mfma_f32_16x16x32_bf16 v[24:27], v[136:139], v[188:191], v[24:27]
	v_mfma_f32_16x16x32_bf16 v[20:23], v[128:131], v[196:199], v[20:23]
	v_mfma_f32_16x16x32_bf16 v[16:19], v[136:139], v[196:199], v[16:19]
	v_mfma_f32_16x16x32_bf16 v[12:15], v[128:131], v[204:207], v[12:15]
	v_mfma_f32_16x16x32_bf16 v[8:11], v[136:139], v[204:207], v[8:11]
	v_mfma_f32_16x16x32_bf16 v[4:7], v[128:131], v[212:215], v[4:7]
	v_mfma_f32_16x16x32_bf16 v[0:3], v[136:139], v[212:215], v[0:3]
	v_mfma_f32_16x16x32_bf16 v[28:31], v[132:135], v[192:195], v[28:31]
	v_mfma_f32_16x16x32_bf16 v[24:27], v[140:143], v[192:195], v[24:27]
	v_mfma_f32_16x16x32_bf16 v[20:23], v[132:135], v[200:203], v[20:23]
	v_mfma_f32_16x16x32_bf16 v[16:19], v[140:143], v[200:203], v[16:19]
	v_mfma_f32_16x16x32_bf16 v[12:15], v[132:135], v[208:211], v[12:15]
	v_mfma_f32_16x16x32_bf16 v[8:11], v[140:143], v[208:211], v[8:11]
	v_mfma_f32_16x16x32_bf16 v[4:7], v[132:135], v[216:219], v[4:7]
	v_mfma_f32_16x16x32_bf16 v[0:3], v[140:143], v[216:219], v[0:3]
	v_mfma_f32_16x16x32_bf16 v[92:95], v[166:169], v[188:191], v[92:95]
	v_mfma_f32_16x16x32_bf16 v[88:91], v[174:177], v[188:191], v[88:91]
	v_mfma_f32_16x16x32_bf16 v[84:87], v[166:169], v[196:199], v[84:87]
	v_mfma_f32_16x16x32_bf16 v[80:83], v[174:177], v[196:199], v[80:83]
	v_mfma_f32_16x16x32_bf16 v[76:79], v[166:169], v[204:207], v[76:79]
	v_mfma_f32_16x16x32_bf16 v[72:75], v[174:177], v[204:207], v[72:75]
	v_mfma_f32_16x16x32_bf16 v[64:67], v[166:169], v[212:215], v[64:67]
	v_mfma_f32_16x16x32_bf16 v[60:63], v[174:177], v[212:215], v[60:63]
	v_mfma_f32_16x16x32_bf16 v[92:95], v[170:173], v[192:195], v[92:95]
	v_mfma_f32_16x16x32_bf16 v[88:91], v[184:187], v[192:195], v[88:91]
	v_mfma_f32_16x16x32_bf16 v[84:87], v[170:173], v[200:203], v[84:87]
	v_mfma_f32_16x16x32_bf16 v[80:83], v[184:187], v[200:203], v[80:83]
	v_mfma_f32_16x16x32_bf16 v[76:79], v[170:173], v[208:211], v[76:79]
	v_mfma_f32_16x16x32_bf16 v[72:75], v[184:187], v[208:211], v[72:75]
	v_mfma_f32_16x16x32_bf16 v[64:67], v[170:173], v[216:219], v[64:67]
	v_mfma_f32_16x16x32_bf16 v[60:63], v[184:187], v[216:219], v[60:63]
	s_setprio 0
	s_barrier
	s_add_i32 s52, s52, 2
	s_add_u32 s46, s46, 0x100
	s_addc_u32 s47, s47, 0
	s_add_u32 s35, s35, 0x100
	s_addc_u32 s45, s45, 0
	s_cmp_gt_u32 s52, 13
	s_cbranch_scc0 .LBB0_564
	s_and_b64 vcc, exec, s[16:17]
	s_cbranch_vccnz .LBB0_568
	v_lshl_add_u32 v166, s44, 8, v178
	s_cmp_lg_u32 s6, 19
	s_mov_b64 s[44:45], -1
	s_cbranch_scc1 .LBB0_569

; #define PG8_STAGE(bufoff, gbase, voff) do { _Pragma("unroll") for (int _i = 0; _i < 2; ++_i) \
;         __builtin_amdgcn_global_load_lds((const unsigned*)((const char*)(gbase) + (voff)[_i]), (PG8_LAS unsigned*)(lds + (bufoff) + ldsw + _i * 8192), 16, 0, 0); } while (0)
; #define PG8_LDA(dst, b, h) do { _Pragma("unroll") for (int m = 0; m < 4; ++m) _Pragma("unroll") for (int k = 0; k < 2; ++k) dst[m][k] = *(const PG8_LAS bf16x8*)(lds + PG8_SA(b, h) + aoff + m * 2048 + k * 1024); } while (0)
; #define PG8_LDB(dst, b, h) do { _Pragma("unroll") for (int n = 0; n < 2; ++n) _Pragma("unroll") for (int k = 0; k < 2; ++k) dst[n][k] = *(const PG8_LAS bf16x8*)(lds + PG8_SB(b, h) + boff + n * 2048 + k * 1024); } while (0)
; #define PG8_MMA(ai, bj, At, Bt) do { __builtin_amdgcn_s_setprio(1); _Pragma("unroll") for (int m = 0; m < 4; ++m) _Pragma("unroll") for (int n = 0; n < 2; ++n) _Pragma("unroll") for (int k = 0; k < 2; ++k) \
;         acc[ai][bj][m][n] = __builtin_amdgcn_mfma_f32_16x16x32_bf16(Bt[n][k], At[m][k], acc[ai][bj][m][n], 0, 0, 0); __builtin_amdgcn_s_setprio(0); } while (0)
; #define PG8_WAIT_V(n) asm volatile("s_waitcnt vmcnt(" #n ")" ::: "memory")
; #define PG8_WAIT_L(n) asm volatile("s_waitcnt lgkmcnt(" #n ")" ::: "memory")
; #define PG8_BAR __builtin_amdgcn_s_barrier()
; #define PG8_SCHED __builtin_amdgcn_sched_barrier(0)
; template <class Epi, class Sched, bool ALIGN_EPI = false, bool SP2 = false>
; __device__ __forceinline__ void gemm_phase(PG8_LAS unsigned char* lds, const Gemm g, const Sched& S, const Epi& E, int tid_in) {
;     ...
;             PG8_LDB(B0, 0, 0); PG8_LDB(B1, 0, 1); PG8_SCHED; PG8_LDA(At, 0, 0); PG8_STAGE(PG8_SA(1, 1), a1 + hstep, voffA);
;             PG8_WAIT_V(8); PG8_WAIT_L(0); PG8_BAR; PG8_MMA(0, 0, At, B0); PG8_MMA(0, 1, At, B1); PG8_BAR; PG8_SCHED;
;             PG8_LDA(At, 0, 1); PG8_STAGE(PG8_SB(0, 0), b2, voffB); PG8_STAGE(PG8_SB(0, 1), b2 + hstep, voffB); PG8_STAGE(PG8_SA(0, 0), a2, voffA);
;             PG8_WAIT_V(8); PG8_WAIT_L(0); PG8_BAR; PG8_MMA(1, 0, At, B0); PG8_MMA(1, 1, At, B1); PG8_BAR; PG8_SCHED;
.LBB0_1062:
	s_add_u32 s0, s44, s46
	s_addc_u32 s1, s45, s47
	s_add_u32 s0, s0, 0x100
	s_addc_u32 s1, s1, 0
	s_add_u32 s48, s78, s46
	s_addc_u32 s49, s79, s47
	s_add_i32 s81, 0, 0x10000
	v_add_u32_e32 v1, s81, v214
	ds_read_b128 v[132:135], v1
	ds_read_b128 v[136:139], v1 offset:1024
	ds_read_b128 v[140:143], v1 offset:2048
	ds_read_b128 v[144:147], v1 offset:3072
	v_add_u32_e32 v1, s74, v214
	ds_read_b128 v[148:151], v1
	ds_read_b128 v[152:155], v1 offset:1024
	ds_read_b128 v[156:159], v1 offset:2048
	ds_read_b128 v[160:163], v1 offset:3072
	s_cmpk_eq_i32 s46, 0x700
	s_cselect_b32 s51, s35, s1
	s_cselect_b32 s50, s67, s0
	s_cselect_b32 s49, s75, s49
	s_cselect_b32 s48, s76, s48
	v_lshl_add_u64 v[2:3], v[208:209], 0, s[46:47]
	s_add_i32 m0, s58, 0xc000
	ds_read_b128 v[164:167], v216
	ds_read_b128 v[168:171], v216 offset:1024
	ds_read_b128 v[172:175], v216 offset:2048
	ds_read_b128 v[176:179], v216 offset:3072
	ds_read_b128 v[180:183], v216 offset:4096
	ds_read_b128 v[184:187], v216 offset:5120
	ds_read_b128 v[218:221], v216 offset:6144
	ds_read_b128 v[222:225], v216 offset:7168
	global_load_lds_dwordx4 v[2:3], off
	v_lshl_add_u64 v[2:3], v[210:211], 0, s[46:47]
	s_add_i32 m0, s58, 0xe000
	s_nop 0
	global_load_lds_dwordx4 v[2:3], off
	s_waitcnt vmcnt(8)
	s_waitcnt lgkmcnt(0)
	s_barrier
	s_setprio 1
	v_mfma_f32_16x16x32_bf16 v[128:131], v[132:135], v[164:167], v[128:131]
	v_mfma_f32_16x16x32_bf16 v[124:127], v[140:143], v[164:167], v[124:127]
	v_mfma_f32_16x16x32_bf16 v[112:115], v[132:135], v[172:175], v[112:115]
	v_mfma_f32_16x16x32_bf16 v[108:111], v[140:143], v[172:175], v[108:111]
	v_mfma_f32_16x16x32_bf16 v[96:99], v[132:135], v[180:183], v[96:99]
	v_mfma_f32_16x16x32_bf16 v[92:95], v[140:143], v[180:183], v[92:95]
	v_mfma_f32_16x16x32_bf16 v[80:83], v[132:135], v[218:221], v[80:83]
	v_mfma_f32_16x16x32_bf16 v[76:79], v[140:143], v[218:221], v[76:79]
	v_mfma_f32_16x16x32_bf16 v[128:131], v[136:139], v[168:171], v[128:131]
	v_mfma_f32_16x16x32_bf16 v[124:127], v[144:147], v[168:171], v[124:127]
	v_mfma_f32_16x16x32_bf16 v[112:115], v[136:139], v[176:179], v[112:115]
	v_mfma_f32_16x16x32_bf16 v[108:111], v[144:147], v[176:179], v[108:111]
	v_mfma_f32_16x16x32_bf16 v[96:99], v[136:139], v[184:187], v[96:99]
	v_mfma_f32_16x16x32_bf16 v[92:95], v[144:147], v[184:187], v[92:95]
	v_mfma_f32_16x16x32_bf16 v[80:83], v[136:139], v[222:225], v[80:83]
	v_mfma_f32_16x16x32_bf16 v[76:79], v[144:147], v[222:225], v[76:79]
	v_mfma_f32_16x16x32_bf16 v[120:123], v[148:151], v[164:167], v[120:123]
	v_mfma_f32_16x16x32_bf16 v[116:119], v[156:159], v[164:167], v[116:119]
	v_mfma_f32_16x16x32_bf16 v[104:107], v[148:151], v[172:175], v[104:107]
	v_mfma_f32_16x16x32_bf16 v[100:103], v[156:159], v[172:175], v[100:103]
	v_mfma_f32_16x16x32_bf16 v[88:91], v[148:151], v[180:183], v[88:91]
	v_mfma_f32_16x16x32_bf16 v[84:87], v[156:159], v[180:183], v[84:87]
	v_mfma_f32_16x16x32_bf16 v[72:75], v[148:151], v[218:221], v[72:75]
	v_mfma_f32_16x16x32_bf16 v[68:71], v[156:159], v[218:221], v[68:71]
	v_mfma_f32_16x16x32_bf16 v[120:123], v[152:155], v[168:171], v[120:123]
	v_mfma_f32_16x16x32_bf16 v[116:119], v[160:163], v[168:171], v[116:119]
	v_mfma_f32_16x16x32_bf16 v[104:107], v[152:155], v[176:179], v[104:107]
	v_mfma_f32_16x16x32_bf16 v[100:103], v[160:163], v[176:179], v[100:103]
	v_mfma_f32_16x16x32_bf16 v[88:91], v[152:155], v[184:187], v[88:91]
	v_mfma_f32_16x16x32_bf16 v[84:87], v[160:163], v[184:187], v[84:87]
	v_mfma_f32_16x16x32_bf16 v[72:75], v[152:155], v[222:225], v[72:75]
	v_mfma_f32_16x16x32_bf16 v[68:71], v[160:163], v[222:225], v[68:71]
	s_setprio 0
	s_barrier
	s_add_i32 s0, s81, s57
	v_lshl_add_u64 v[226:227], s[48:49], 0, v[190:191]
	s_mov_b32 m0, s0
	ds_read_b128 v[164:167], v216 offset:16384
	ds_read_b128 v[168:171], v216 offset:17408
	ds_read_b128 v[172:175], v216 offset:18432
	ds_read_b128 v[176:179], v216 offset:19456
	ds_read_b128 v[180:183], v216 offset:20480
	ds_read_b128 v[184:187], v216 offset:21504
	ds_read_b128 v[218:221], v216 offset:22528
	ds_read_b128 v[222:225], v216 offset:23552
	global_load_lds_dwordx4 v[226:227], off
	s_add_i32 m0, s0, 0x2000
	s_add_u32 s0, s48, 0x40000
	v_lshl_add_u64 v[228:229], s[48:49], 0, v[194:195]
	s_addc_u32 s1, s49, 0
	s_add_i32 s81, s74, s57
	global_load_lds_dwordx4 v[228:229], off
	v_lshl_add_u64 v[2:3], s[0:1], 0, v[190:191]
	s_mov_b32 m0, s81
	v_lshl_add_u64 v[232:233], s[50:51], 0, v[188:189]
	global_load_lds_dwordx4 v[2:3], off
	v_lshl_add_u64 v[2:3], s[0:1], 0, v[194:195]
	s_add_i32 m0, s81, 0x2000
	v_lshl_add_u64 v[234:235], s[50:51], 0, v[192:193]
	global_load_lds_dwordx4 v[2:3], off
	s_mov_b32 m0, s58
	s_nop 0
	global_load_lds_dwordx4 v[232:233], off
	s_mov_b32 m0, s59
	s_nop 0
	global_load_lds_dwordx4 v[234:235], off
	s_waitcnt vmcnt(8)
	s_waitcnt lgkmcnt(0)
	s_barrier
; #define PG8_STAGE(bufoff, gbase, voff) do { _Pragma("unroll") for (int _i = 0; _i < 2; ++_i) \
;         __builtin_amdgcn_global_load_lds((const unsigned*)((const char*)(gbase) + (voff)[_i]), (PG8_LAS unsigned*)(lds + (bufoff) + ldsw + _i * 8192), 16, 0, 0); } while (0)
; #define PG8_LDA(dst, b, h) do { _Pragma("unroll") for (int m = 0; m < 4; ++m) _Pragma("unroll") for (int k = 0; k < 2; ++k) dst[m][k] = *(const PG8_LAS bf16x8*)(lds + PG8_SA(b, h) + aoff + m * 2048 + k * 1024); } while (0)
; #define PG8_LDB(dst, b, h) do { _Pragma("unroll") for (int n = 0; n < 2; ++n) _Pragma("unroll") for (int k = 0; k < 2; ++k) dst[n][k] = *(const PG8_LAS bf16x8*)(lds + PG8_SB(b, h) + boff + n * 2048 + k * 1024); } while (0)
; #define PG8_MMA(ai, bj, At, Bt) do { __builtin_amdgcn_s_setprio(1); _Pragma("unroll") for (int m = 0; m < 4; ++m) _Pragma("unroll") for (int n = 0; n < 2; ++n) _Pragma("unroll") for (int k = 0; k < 2; ++k) \
;         acc[ai][bj][m][n] = __builtin_amdgcn_mfma_f32_16x16x32_bf16(Bt[n][k], At[m][k], acc[ai][bj][m][n], 0, 0, 0); __builtin_amdgcn_s_setprio(0); } while (0)
; #define PG8_WAIT_V(n) asm volatile("s_waitcnt vmcnt(" #n ")" ::: "memory")
; #define PG8_WAIT_L(n) asm volatile("s_waitcnt lgkmcnt(" #n ")" ::: "memory")
; #define PG8_BAR __builtin_amdgcn_s_barrier()
; #define PG8_SCHED __builtin_amdgcn_sched_barrier(0)
; template <class Epi, class Sched, bool ALIGN_EPI = false, bool SP2 = false>
; __device__ __forceinline__ void gemm_phase(PG8_LAS unsigned char* lds, const Gemm g, const Sched& S, const Epi& E, int tid_in) {
;     ...
;             PG8_WAIT_V(8); PG8_WAIT_L(0); PG8_BAR; PG8_MMA(1, 0, At, B0); PG8_MMA(1, 1, At, B1); PG8_BAR; PG8_SCHED;
;             PG8_LDB(B0, 1, 0); PG8_LDB(B1, 1, 1); PG8_SCHED; PG8_LDA(At, 1, 0); PG8_STAGE(PG8_SA(0, 1), a2 + hstep, voffA);
;             PG8_WAIT_V(8); PG8_WAIT_L(0); PG8_BAR; PG8_MMA(0, 0, At, B0); PG8_MMA(0, 1, At, B1); PG8_BAR; PG8_SCHED;
	s_setprio 1
	v_mfma_f32_16x16x32_bf16 v[64:67], v[132:135], v[164:167], v[64:67]
	v_mfma_f32_16x16x32_bf16 v[60:63], v[140:143], v[164:167], v[60:63]
	v_mfma_f32_16x16x32_bf16 v[48:51], v[132:135], v[172:175], v[48:51]
	v_mfma_f32_16x16x32_bf16 v[44:47], v[140:143], v[172:175], v[44:47]
	v_mfma_f32_16x16x32_bf16 v[32:35], v[132:135], v[180:183], v[32:35]
	v_mfma_f32_16x16x32_bf16 v[28:31], v[140:143], v[180:183], v[28:31]
	v_mfma_f32_16x16x32_bf16 v[16:19], v[132:135], v[218:221], v[16:19]
	v_mfma_f32_16x16x32_bf16 v[12:15], v[140:143], v[218:221], v[12:15]
	v_mfma_f32_16x16x32_bf16 v[64:67], v[136:139], v[168:171], v[64:67]
	v_mfma_f32_16x16x32_bf16 v[60:63], v[144:147], v[168:171], v[60:63]
	v_mfma_f32_16x16x32_bf16 v[48:51], v[136:139], v[176:179], v[48:51]
	v_mfma_f32_16x16x32_bf16 v[44:47], v[144:147], v[176:179], v[44:47]
	v_mfma_f32_16x16x32_bf16 v[32:35], v[136:139], v[184:187], v[32:35]
	v_mfma_f32_16x16x32_bf16 v[28:31], v[144:147], v[184:187], v[28:31]
	v_mfma_f32_16x16x32_bf16 v[16:19], v[136:139], v[222:225], v[16:19]
	v_mfma_f32_16x16x32_bf16 v[12:15], v[144:147], v[222:225], v[12:15]
	v_mfma_f32_16x16x32_bf16 v[56:59], v[148:151], v[164:167], v[56:59]
	v_mfma_f32_16x16x32_bf16 v[52:55], v[156:159], v[164:167], v[52:55]
	v_mfma_f32_16x16x32_bf16 v[40:43], v[148:151], v[172:175], v[40:43]
	v_mfma_f32_16x16x32_bf16 v[36:39], v[156:159], v[172:175], v[36:39]
	v_mfma_f32_16x16x32_bf16 v[24:27], v[148:151], v[180:183], v[24:27]
	v_mfma_f32_16x16x32_bf16 v[20:23], v[156:159], v[180:183], v[20:23]
	v_mfma_f32_16x16x32_bf16 v[8:11], v[148:151], v[218:221], v[8:11]
	v_mfma_f32_16x16x32_bf16 v[2:5], v[156:159], v[218:221], v[4:7]
	v_mfma_f32_16x16x32_bf16 v[56:59], v[152:155], v[168:171], v[56:59]
	v_mfma_f32_16x16x32_bf16 v[52:55], v[160:163], v[168:171], v[52:55]
	v_mfma_f32_16x16x32_bf16 v[40:43], v[152:155], v[176:179], v[40:43]
	v_mfma_f32_16x16x32_bf16 v[36:39], v[160:163], v[176:179], v[36:39]
	v_mfma_f32_16x16x32_bf16 v[24:27], v[152:155], v[184:187], v[24:27]
	v_mfma_f32_16x16x32_bf16 v[20:23], v[160:163], v[184:187], v[20:23]
	v_mfma_f32_16x16x32_bf16 v[8:11], v[152:155], v[222:225], v[8:11]
	v_mfma_f32_16x16x32_bf16 v[2:5], v[160:163], v[222:225], v[2:5]
	s_setprio 0
	s_barrier
	s_add_i32 s81, 0, 0x18000
	v_add_u32_e32 v1, s81, v214
	s_add_i32 s82, 0, 0x1c000
	ds_read_b128 v[132:135], v1
	ds_read_b128 v[136:139], v1 offset:1024
	ds_read_b128 v[140:143], v1 offset:2048
	ds_read_b128 v[144:147], v1 offset:3072
	v_add_u32_e32 v1, s82, v214
	ds_read_b128 v[148:151], v1
	ds_read_b128 v[152:155], v1 offset:1024
	ds_read_b128 v[156:159], v1 offset:2048
	ds_read_b128 v[160:163], v1 offset:3072
	s_add_u32 s0, s50, 0x40000
	s_addc_u32 s1, s51, 0
	s_mov_b32 m0, s60
	v_lshl_add_u64 v[6:7], s[0:1], 0, v[188:189]
	ds_read_b128 v[164:167], v216 offset:32768
	ds_read_b128 v[168:171], v216 offset:33792
	ds_read_b128 v[172:175], v216 offset:34816
	ds_read_b128 v[176:179], v216 offset:35840
	ds_read_b128 v[180:183], v216 offset:36864
	ds_read_b128 v[184:187], v216 offset:37888
	ds_read_b128 v[218:221], v216 offset:38912
	ds_read_b128 v[222:225], v216 offset:39936
	global_load_lds_dwordx4 v[6:7], off
	v_lshl_add_u64 v[6:7], s[0:1], 0, v[192:193]
	s_mov_b32 m0, s61
	s_nop 0
	global_load_lds_dwordx4 v[6:7], off
	s_waitcnt vmcnt(8)
	s_waitcnt lgkmcnt(0)
	s_barrier
	s_setprio 1
	v_mfma_f32_16x16x32_bf16 v[128:131], v[132:135], v[164:167], v[128:131]
	v_mfma_f32_16x16x32_bf16 v[124:127], v[140:143], v[164:167], v[124:127]
	v_mfma_f32_16x16x32_bf16 v[112:115], v[132:135], v[172:175], v[112:115]
	v_mfma_f32_16x16x32_bf16 v[108:111], v[140:143], v[172:175], v[108:111]
	v_mfma_f32_16x16x32_bf16 v[96:99], v[132:135], v[180:183], v[96:99]
	v_mfma_f32_16x16x32_bf16 v[92:95], v[140:143], v[180:183], v[92:95]
	v_mfma_f32_16x16x32_bf16 v[80:83], v[132:135], v[218:221], v[80:83]
	v_mfma_f32_16x16x32_bf16 v[76:79], v[140:143], v[218:221], v[76:79]
	v_mfma_f32_16x16x32_bf16 v[128:131], v[136:139], v[168:171], v[128:131]
	v_mfma_f32_16x16x32_bf16 v[124:127], v[144:147], v[168:171], v[124:127]
	v_mfma_f32_16x16x32_bf16 v[112:115], v[136:139], v[176:179], v[112:115]
	v_mfma_f32_16x16x32_bf16 v[108:111], v[144:147], v[176:179], v[108:111]
	v_mfma_f32_16x16x32_bf16 v[96:99], v[136:139], v[184:187], v[96:99]
	v_mfma_f32_16x16x32_bf16 v[92:95], v[144:147], v[184:187], v[92:95]
	v_mfma_f32_16x16x32_bf16 v[80:83], v[136:139], v[222:225], v[80:83]
	v_mfma_f32_16x16x32_bf16 v[76:79], v[144:147], v[222:225], v[76:79]
	v_mfma_f32_16x16x32_bf16 v[120:123], v[148:151], v[164:167], v[120:123]
	v_mfma_f32_16x16x32_bf16 v[116:119], v[156:159], v[164:167], v[116:119]
	v_mfma_f32_16x16x32_bf16 v[104:107], v[148:151], v[172:175], v[104:107]
	v_mfma_f32_16x16x32_bf16 v[100:103], v[156:159], v[172:175], v[100:103]
	v_mfma_f32_16x16x32_bf16 v[88:91], v[148:151], v[180:183], v[88:91]
	v_mfma_f32_16x16x32_bf16 v[84:87], v[156:159], v[180:183], v[84:87]
	v_mfma_f32_16x16x32_bf16 v[72:75], v[148:151], v[218:221], v[72:75]
	v_mfma_f32_16x16x32_bf16 v[68:71], v[156:159], v[218:221], v[68:71]
	v_mfma_f32_16x16x32_bf16 v[120:123], v[152:155], v[168:171], v[120:123]
	v_mfma_f32_16x16x32_bf16 v[116:119], v[160:163], v[168:171], v[116:119]
	v_mfma_f32_16x16x32_bf16 v[104:107], v[152:155], v[176:179], v[104:107]
	v_mfma_f32_16x16x32_bf16 v[100:103], v[160:163], v[176:179], v[100:103]
	v_mfma_f32_16x16x32_bf16 v[88:91], v[152:155], v[184:187], v[88:91]
	v_mfma_f32_16x16x32_bf16 v[84:87], v[160:163], v[184:187], v[84:87]
	v_mfma_f32_16x16x32_bf16 v[72:75], v[152:155], v[222:225], v[72:75]
	v_mfma_f32_16x16x32_bf16 v[68:71], v[160:163], v[222:225], v[68:71]
	s_setprio 0
	s_barrier
; #define PG8_STAGE(bufoff, gbase, voff) do { _Pragma("unroll") for (int _i = 0; _i < 2; ++_i) \
;         __builtin_amdgcn_global_load_lds((const unsigned*)((const char*)(gbase) + (voff)[_i]), (PG8_LAS unsigned*)(lds + (bufoff) + ldsw + _i * 8192), 16, 0, 0); } while (0)
; #define PG8_LDA(dst, b, h) do { _Pragma("unroll") for (int m = 0; m < 4; ++m) _Pragma("unroll") for (int k = 0; k < 2; ++k) dst[m][k] = *(const PG8_LAS bf16x8*)(lds + PG8_SA(b, h) + aoff + m * 2048 + k * 1024); } while (0)
; #define PG8_MMA(ai, bj, At, Bt) do { __builtin_amdgcn_s_setprio(1); _Pragma("unroll") for (int m = 0; m < 4; ++m) _Pragma("unroll") for (int n = 0; n < 2; ++n) _Pragma("unroll") for (int k = 0; k < 2; ++k) \
;         acc[ai][bj][m][n] = __builtin_amdgcn_mfma_f32_16x16x32_bf16(Bt[n][k], At[m][k], acc[ai][bj][m][n], 0, 0, 0); __builtin_amdgcn_s_setprio(0); } while (0)
; #define PG8_WAIT_V(n) asm volatile("s_waitcnt vmcnt(" #n ")" ::: "memory")
; #define PG8_WAIT_L(n) asm volatile("s_waitcnt lgkmcnt(" #n ")" ::: "memory")
; #define PG8_BAR __builtin_amdgcn_s_barrier()
; #define PG8_SCHED __builtin_amdgcn_sched_barrier(0)
; template <class Epi, class Sched, bool ALIGN_EPI = false, bool SP2 = false>
; __device__ __forceinline__ void gemm_phase(PG8_LAS unsigned char* lds, const Gemm g, const Sched& S, const Epi& E, int tid_in) {
;     ...
;             PG8_LDA(At, 1, 1); PG8_STAGE(PG8_SB(1, 0), b3, voffB); PG8_STAGE(PG8_SB(1, 1), b3 + hstep, voffB); PG8_STAGE(PG8_SA(1, 0), a3, voffA);
;             PG8_WAIT_V(8); PG8_WAIT_L(0); PG8_BAR; PG8_MMA(1, 0, At, B0); PG8_MMA(1, 1, At, B1); PG8_BAR; PG8_SCHED;
	s_add_i32 s0, s81, s57
	v_lshl_add_u64 v[6:7], v[226:227], 0, s[12:13]
	s_mov_b32 m0, s0
	ds_read_b128 v[164:167], v216 offset:49152
	ds_read_b128 v[168:171], v216 offset:50176
	ds_read_b128 v[172:175], v216 offset:51200
	ds_read_b128 v[176:179], v216 offset:52224
	ds_read_b128 v[180:183], v216 offset:53248
	ds_read_b128 v[184:187], v216 offset:54272
	ds_read_b128 v[218:221], v216 offset:55296
	ds_read_b128 v[222:225], v216 offset:56320
	global_load_lds_dwordx4 v[6:7], off
	s_add_i32 m0, s0, 0x2000
	s_add_u32 s0, s48, 0x40080
	v_lshl_add_u64 v[6:7], v[228:229], 0, s[12:13]
	s_addc_u32 s1, s49, 0
	s_add_i32 s48, s82, s57
	global_load_lds_dwordx4 v[6:7], off
	v_lshl_add_u64 v[6:7], s[0:1], 0, v[190:191]
	s_mov_b32 m0, s48
	s_nop 0
	global_load_lds_dwordx4 v[6:7], off
	v_lshl_add_u64 v[6:7], s[0:1], 0, v[194:195]
	s_add_i32 m0, s48, 0x2000
	s_nop 0
	global_load_lds_dwordx4 v[6:7], off
	v_lshl_add_u64 v[6:7], v[232:233], 0, s[12:13]
	s_mov_b32 m0, s64
	s_nop 0
	global_load_lds_dwordx4 v[6:7], off
	v_lshl_add_u64 v[6:7], v[234:235], 0, s[12:13]
	s_mov_b32 m0, s65
	s_nop 0
	global_load_lds_dwordx4 v[6:7], off
	s_waitcnt vmcnt(8)
	s_waitcnt lgkmcnt(0)
	s_barrier
	s_setprio 1
	v_mfma_f32_16x16x32_bf16 v[64:67], v[132:135], v[164:167], v[64:67]
	v_mfma_f32_16x16x32_bf16 v[60:63], v[140:143], v[164:167], v[60:63]
	v_mfma_f32_16x16x32_bf16 v[48:51], v[132:135], v[172:175], v[48:51]
	v_mfma_f32_16x16x32_bf16 v[44:47], v[140:143], v[172:175], v[44:47]
	v_mfma_f32_16x16x32_bf16 v[32:35], v[132:135], v[180:183], v[32:35]
	v_mfma_f32_16x16x32_bf16 v[28:31], v[140:143], v[180:183], v[28:31]
	v_mfma_f32_16x16x32_bf16 v[16:19], v[132:135], v[218:221], v[16:19]
	v_mfma_f32_16x16x32_bf16 v[12:15], v[140:143], v[218:221], v[12:15]
	v_mfma_f32_16x16x32_bf16 v[64:67], v[136:139], v[168:171], v[64:67]
	v_mfma_f32_16x16x32_bf16 v[60:63], v[144:147], v[168:171], v[60:63]
	v_mfma_f32_16x16x32_bf16 v[48:51], v[136:139], v[176:179], v[48:51]
	v_mfma_f32_16x16x32_bf16 v[44:47], v[144:147], v[176:179], v[44:47]
	v_mfma_f32_16x16x32_bf16 v[32:35], v[136:139], v[184:187], v[32:35]
	v_mfma_f32_16x16x32_bf16 v[28:31], v[144:147], v[184:187], v[28:31]
	v_mfma_f32_16x16x32_bf16 v[16:19], v[136:139], v[222:225], v[16:19]
	v_mfma_f32_16x16x32_bf16 v[12:15], v[144:147], v[222:225], v[12:15]
	v_mfma_f32_16x16x32_bf16 v[56:59], v[148:151], v[164:167], v[56:59]
	v_mfma_f32_16x16x32_bf16 v[52:55], v[156:159], v[164:167], v[52:55]
	v_mfma_f32_16x16x32_bf16 v[40:43], v[148:151], v[172:175], v[40:43]
	v_mfma_f32_16x16x32_bf16 v[36:39], v[156:159], v[172:175], v[36:39]
	v_mfma_f32_16x16x32_bf16 v[24:27], v[148:151], v[180:183], v[24:27]
	v_mfma_f32_16x16x32_bf16 v[20:23], v[156:159], v[180:183], v[20:23]
	v_mfma_f32_16x16x32_bf16 v[6:9], v[148:151], v[218:221], v[8:11]
	v_mfma_f32_16x16x32_bf16 v[2:5], v[156:159], v[218:221], v[2:5]
	v_mfma_f32_16x16x32_bf16 v[56:59], v[152:155], v[168:171], v[56:59]
	v_mfma_f32_16x16x32_bf16 v[52:55], v[160:163], v[168:171], v[52:55]
	v_mfma_f32_16x16x32_bf16 v[40:43], v[152:155], v[176:179], v[40:43]
	v_mfma_f32_16x16x32_bf16 v[36:39], v[160:163], v[176:179], v[36:39]
	v_mfma_f32_16x16x32_bf16 v[24:27], v[152:155], v[184:187], v[24:27]
	v_mfma_f32_16x16x32_bf16 v[20:23], v[160:163], v[184:187], v[20:23]
	v_mfma_f32_16x16x32_bf16 v[8:11], v[152:155], v[222:225], v[6:9]
	v_mfma_f32_16x16x32_bf16 v[4:7], v[160:163], v[222:225], v[2:5]
	s_setprio 0
	s_barrier
	s_add_i32 s80, s80, 2
	s_add_u32 s46, s46, 0x100
	s_addc_u32 s47, s47, 0
	s_cmp_gt_u32 s80, 13
	s_cbranch_scc1 .LBB0_1068

; #define PG8_STAGE(bufoff, gbase, voff) do { _Pragma("unroll") for (int _i = 0; _i < 2; ++_i) \
;         __builtin_amdgcn_global_load_lds((const unsigned*)((const char*)(gbase) + (voff)[_i]), (PG8_LAS unsigned*)(lds + (bufoff) + ldsw + _i * 8192), 16, 0, 0); } while (0)
; #define PG8_LDA(dst, b, h) do { _Pragma("unroll") for (int m = 0; m < 4; ++m) _Pragma("unroll") for (int k = 0; k < 2; ++k) dst[m][k] = *(const PG8_LAS bf16x8*)(lds + PG8_SA(b, h) + aoff + m * 2048 + k * 1024); } while (0)
; #define PG8_LDB(dst, b, h) do { _Pragma("unroll") for (int n = 0; n < 2; ++n) _Pragma("unroll") for (int k = 0; k < 2; ++k) dst[n][k] = *(const PG8_LAS bf16x8*)(lds + PG8_SB(b, h) + boff + n * 2048 + k * 1024); } while (0)
; #define PG8_MMA(ai, bj, At, Bt) do { __builtin_amdgcn_s_setprio(1); _Pragma("unroll") for (int m = 0; m < 4; ++m) _Pragma("unroll") for (int n = 0; n < 2; ++n) _Pragma("unroll") for (int k = 0; k < 2; ++k) \
;         acc[ai][bj][m][n] = __builtin_amdgcn_mfma_f32_16x16x32_bf16(Bt[n][k], At[m][k], acc[ai][bj][m][n], 0, 0, 0); __builtin_amdgcn_s_setprio(0); } while (0)
; #define PG8_WAIT_V(n) asm volatile("s_waitcnt vmcnt(" #n ")" ::: "memory")
; #define PG8_WAIT_L(n) asm volatile("s_waitcnt lgkmcnt(" #n ")" ::: "memory")
; #define PG8_BAR __builtin_amdgcn_s_barrier()
; #define PG8_SCHED __builtin_amdgcn_sched_barrier(0)
; template <class Epi, class Sched, bool ALIGN_EPI = false, bool SP2 = false>
; __device__ __forceinline__ void gemm_phase(PG8_LAS unsigned char* lds, const Gemm g, const Sched& S, const Epi& E, int tid_in) {
;     ...
;             PG8_LDB(B0, 0, 0); PG8_LDB(B1, 0, 1); PG8_SCHED; PG8_LDA(At, 0, 0); PG8_STAGE(PG8_SA(1, 1), a1 + hstep, voffA);
;             PG8_WAIT_V(8); PG8_WAIT_L(0); PG8_BAR; PG8_MMA(0, 0, At, B0); PG8_MMA(0, 1, At, B1); PG8_BAR; PG8_SCHED;
;             PG8_LDA(At, 0, 1); PG8_STAGE(PG8_SB(0, 0), b2, voffB); PG8_STAGE(PG8_SB(0, 1), b2 + hstep, voffB); PG8_STAGE(PG8_SA(0, 0), a2, voffA);
;             PG8_WAIT_V(8); PG8_WAIT_L(0); PG8_BAR; PG8_MMA(1, 0, At, B0); PG8_MMA(1, 1, At, B1); PG8_BAR; PG8_SCHED;
.LBB0_1148:
	s_add_u32 s34, s30, 0xfffc0080
	s_addc_u32 s35, s31, -1
	s_cmp_eq_u32 s60, 12
	s_cselect_b32 s37, s23, s35
	s_cselect_b32 s36, s29, s34
	s_cselect_b32 s35, s21, s59
	s_cselect_b32 s34, s57, s58
	s_add_i32 m0, s1, 0xc000
	ds_read_b128 v[128:131], v191
	global_load_lds_dwordx4 v160, s[30:31]
	s_add_i32 m0, s1, 0xe000
	ds_read_b128 v[132:135], v191 offset:1024
	global_load_lds_dwordx4 v162, s[30:31]
	ds_read_b128 v[136:139], v191 offset:2048
	ds_read_b128 v[140:143], v191 offset:3072
	ds_read_b128 v[144:147], v192
	ds_read_b128 v[148:151], v192 offset:1024
	ds_read_b128 v[168:171], v192 offset:2048
	ds_read_b128 v[172:175], v192 offset:3072
	ds_read_b128 v[176:179], v193
	ds_read_b128 v[180:183], v193 offset:1024
	ds_read_b128 v[194:197], v193 offset:2048
	ds_read_b128 v[198:201], v193 offset:3072
	ds_read_b128 v[202:205], v193 offset:4096
	ds_read_b128 v[206:209], v193 offset:5120
	ds_read_b128 v[210:213], v193 offset:6144
	ds_read_b128 v[214:217], v193 offset:7168
	s_waitcnt vmcnt(8)
	s_waitcnt lgkmcnt(0)
	s_barrier
	s_setprio 1
	v_mfma_f32_16x16x32_bf16 v[124:127], v[128:131], v[176:179], v[124:127]
	v_mfma_f32_16x16x32_bf16 v[120:123], v[136:139], v[176:179], v[120:123]
	v_mfma_f32_16x16x32_bf16 v[108:111], v[128:131], v[194:197], v[108:111]
	v_mfma_f32_16x16x32_bf16 v[104:107], v[136:139], v[194:197], v[104:107]
	v_mfma_f32_16x16x32_bf16 v[92:95], v[128:131], v[202:205], v[92:95]
	v_mfma_f32_16x16x32_bf16 v[88:91], v[136:139], v[202:205], v[88:91]
	v_mfma_f32_16x16x32_bf16 v[76:79], v[128:131], v[210:213], v[76:79]
	v_mfma_f32_16x16x32_bf16 v[72:75], v[136:139], v[210:213], v[72:75]
	v_mfma_f32_16x16x32_bf16 v[124:127], v[132:135], v[180:183], v[124:127]
	v_mfma_f32_16x16x32_bf16 v[120:123], v[140:143], v[180:183], v[120:123]
	v_mfma_f32_16x16x32_bf16 v[108:111], v[132:135], v[198:201], v[108:111]
	v_mfma_f32_16x16x32_bf16 v[104:107], v[140:143], v[198:201], v[104:107]
	v_mfma_f32_16x16x32_bf16 v[92:95], v[132:135], v[206:209], v[92:95]
	v_mfma_f32_16x16x32_bf16 v[88:91], v[140:143], v[206:209], v[88:91]
	v_mfma_f32_16x16x32_bf16 v[76:79], v[132:135], v[214:217], v[76:79]
	v_mfma_f32_16x16x32_bf16 v[72:75], v[140:143], v[214:217], v[72:75]
	v_mfma_f32_16x16x32_bf16 v[116:119], v[144:147], v[176:179], v[116:119]
	v_mfma_f32_16x16x32_bf16 v[112:115], v[168:171], v[176:179], v[112:115]
	v_mfma_f32_16x16x32_bf16 v[100:103], v[144:147], v[194:197], v[100:103]
	v_mfma_f32_16x16x32_bf16 v[96:99], v[168:171], v[194:197], v[96:99]
	v_mfma_f32_16x16x32_bf16 v[84:87], v[144:147], v[202:205], v[84:87]
	v_mfma_f32_16x16x32_bf16 v[80:83], v[168:171], v[202:205], v[80:83]
	v_mfma_f32_16x16x32_bf16 v[68:71], v[144:147], v[210:213], v[68:71]
	v_mfma_f32_16x16x32_bf16 v[64:67], v[168:171], v[210:213], v[64:67]
	v_mfma_f32_16x16x32_bf16 v[116:119], v[148:151], v[180:183], v[116:119]
	v_mfma_f32_16x16x32_bf16 v[112:115], v[172:175], v[180:183], v[112:115]
	v_mfma_f32_16x16x32_bf16 v[100:103], v[148:151], v[198:201], v[100:103]
	v_mfma_f32_16x16x32_bf16 v[96:99], v[172:175], v[198:201], v[96:99]
	v_mfma_f32_16x16x32_bf16 v[84:87], v[148:151], v[206:209], v[84:87]
	v_mfma_f32_16x16x32_bf16 v[80:83], v[172:175], v[206:209], v[80:83]
	v_mfma_f32_16x16x32_bf16 v[68:71], v[148:151], v[214:217], v[68:71]
	v_mfma_f32_16x16x32_bf16 v[64:67], v[172:175], v[214:217], v[64:67]
	s_setprio 0
	s_barrier
	s_add_u32 s98, s34, s16
	s_addc_u32 s99, s35, s17
	s_add_u32 s100, s36, s16
	s_addc_u32 s101, s37, s17
	s_add_i32 s61, s54, s0
	s_mov_b32 m0, s61
	ds_read_b128 v[176:179], v193 offset:16384
	global_load_lds_dwordx4 v154, s[34:35]
	s_add_i32 m0, s61, 0x2000
	s_add_u32 s62, s34, 0x40000
	s_addc_u32 s63, s35, 0
	s_add_i32 s61, s55, s0
	global_load_lds_dwordx4 v158, s[34:35]
	s_mov_b32 m0, s61
	ds_read_b128 v[180:183], v193 offset:17408
	global_load_lds_dwordx4 v154, s[62:63]
	s_add_i32 m0, s61, 0x2000
	ds_read_b128 v[194:197], v193 offset:18432
	global_load_lds_dwordx4 v158, s[62:63]
	s_mov_b32 m0, s1
	ds_read_b128 v[198:201], v193 offset:19456
	global_load_lds_dwordx4 v152, s[36:37]
	s_mov_b32 m0, s46
	ds_read_b128 v[202:205], v193 offset:20480
	global_load_lds_dwordx4 v156, s[36:37]
	ds_read_b128 v[206:209], v193 offset:21504
	ds_read_b128 v[210:213], v193 offset:22528
	ds_read_b128 v[214:217], v193 offset:23552
	s_waitcnt vmcnt(8)
	s_waitcnt lgkmcnt(0)
	s_barrier
	s_setprio 1
	v_mfma_f32_16x16x32_bf16 v[60:63], v[128:131], v[176:179], v[60:63]
	v_mfma_f32_16x16x32_bf16 v[56:59], v[136:139], v[176:179], v[56:59]
	v_mfma_f32_16x16x32_bf16 v[44:47], v[128:131], v[194:197], v[44:47]
	v_mfma_f32_16x16x32_bf16 v[40:43], v[136:139], v[194:197], v[40:43]
	v_mfma_f32_16x16x32_bf16 v[28:31], v[128:131], v[202:205], v[28:31]
	v_mfma_f32_16x16x32_bf16 v[24:27], v[136:139], v[202:205], v[24:27]
	v_mfma_f32_16x16x32_bf16 v[12:15], v[128:131], v[210:213], v[12:15]
	v_mfma_f32_16x16x32_bf16 v[8:11], v[136:139], v[210:213], v[8:11]
	v_mfma_f32_16x16x32_bf16 v[60:63], v[132:135], v[180:183], v[60:63]
	v_mfma_f32_16x16x32_bf16 v[56:59], v[140:143], v[180:183], v[56:59]
	v_mfma_f32_16x16x32_bf16 v[44:47], v[132:135], v[198:201], v[44:47]
	v_mfma_f32_16x16x32_bf16 v[40:43], v[140:143], v[198:201], v[40:43]
	v_mfma_f32_16x16x32_bf16 v[28:31], v[132:135], v[206:209], v[28:31]
	v_mfma_f32_16x16x32_bf16 v[24:27], v[140:143], v[206:209], v[24:27]
	v_mfma_f32_16x16x32_bf16 v[12:15], v[132:135], v[214:217], v[12:15]
	v_mfma_f32_16x16x32_bf16 v[8:11], v[140:143], v[214:217], v[8:11]
	v_mfma_f32_16x16x32_bf16 v[52:55], v[144:147], v[176:179], v[52:55]
	v_mfma_f32_16x16x32_bf16 v[48:51], v[168:171], v[176:179], v[48:51]
	v_mfma_f32_16x16x32_bf16 v[36:39], v[144:147], v[194:197], v[36:39]
	v_mfma_f32_16x16x32_bf16 v[32:35], v[168:171], v[194:197], v[32:35]
	v_mfma_f32_16x16x32_bf16 v[20:23], v[144:147], v[202:205], v[20:23]
	v_mfma_f32_16x16x32_bf16 v[16:19], v[168:171], v[202:205], v[16:19]
	v_mfma_f32_16x16x32_bf16 v[4:7], v[144:147], v[210:213], v[4:7]
	v_mfma_f32_16x16x32_bf16 v[0:3], v[168:171], v[210:213], v[0:3]
	v_mfma_f32_16x16x32_bf16 v[52:55], v[148:151], v[180:183], v[52:55]
	v_mfma_f32_16x16x32_bf16 v[48:51], v[172:175], v[180:183], v[48:51]
	v_mfma_f32_16x16x32_bf16 v[36:39], v[148:151], v[198:201], v[36:39]
	v_mfma_f32_16x16x32_bf16 v[32:35], v[172:175], v[198:201], v[32:35]
	v_mfma_f32_16x16x32_bf16 v[20:23], v[148:151], v[206:209], v[20:23]
	v_mfma_f32_16x16x32_bf16 v[16:19], v[172:175], v[206:209], v[16:19]
	v_mfma_f32_16x16x32_bf16 v[4:7], v[148:151], v[214:217], v[4:7]
	v_mfma_f32_16x16x32_bf16 v[0:3], v[172:175], v[214:217], v[0:3]
	s_setprio 0
	s_barrier
; #define PG8_STAGE(bufoff, gbase, voff) do { _Pragma("unroll") for (int _i = 0; _i < 2; ++_i) \
;         __builtin_amdgcn_global_load_lds((const unsigned*)((const char*)(gbase) + (voff)[_i]), (PG8_LAS unsigned*)(lds + (bufoff) + ldsw + _i * 8192), 16, 0, 0); } while (0)
; #define PG8_LDA(dst, b, h) do { _Pragma("unroll") for (int m = 0; m < 4; ++m) _Pragma("unroll") for (int k = 0; k < 2; ++k) dst[m][k] = *(const PG8_LAS bf16x8*)(lds + PG8_SA(b, h) + aoff + m * 2048 + k * 1024); } while (0)
; #define PG8_LDB(dst, b, h) do { _Pragma("unroll") for (int n = 0; n < 2; ++n) _Pragma("unroll") for (int k = 0; k < 2; ++k) dst[n][k] = *(const PG8_LAS bf16x8*)(lds + PG8_SB(b, h) + boff + n * 2048 + k * 1024); } while (0)
; #define PG8_MMA(ai, bj, At, Bt) do { __builtin_amdgcn_s_setprio(1); _Pragma("unroll") for (int m = 0; m < 4; ++m) _Pragma("unroll") for (int n = 0; n < 2; ++n) _Pragma("unroll") for (int k = 0; k < 2; ++k) \
;         acc[ai][bj][m][n] = __builtin_amdgcn_mfma_f32_16x16x32_bf16(Bt[n][k], At[m][k], acc[ai][bj][m][n], 0, 0, 0); __builtin_amdgcn_s_setprio(0); } while (0)
; #define PG8_WAIT_V(n) asm volatile("s_waitcnt vmcnt(" #n ")" ::: "memory")
; #define PG8_WAIT_L(n) asm volatile("s_waitcnt lgkmcnt(" #n ")" ::: "memory")
; #define PG8_BAR __builtin_amdgcn_s_barrier()
; #define PG8_SCHED __builtin_amdgcn_sched_barrier(0)
; template <class Epi, class Sched, bool ALIGN_EPI = false, bool SP2 = false>
; __device__ __forceinline__ void gemm_phase(PG8_LAS unsigned char* lds, const Gemm g, const Sched& S, const Epi& E, int tid_in) {
;     ...
;             PG8_LDB(B0, 1, 0); PG8_LDB(B1, 1, 1); PG8_SCHED; PG8_LDA(At, 1, 0); PG8_STAGE(PG8_SA(0, 1), a2 + hstep, voffA);
;             PG8_WAIT_V(8); PG8_WAIT_L(0); PG8_BAR; PG8_MMA(0, 0, At, B0); PG8_MMA(0, 1, At, B1); PG8_BAR; PG8_SCHED;
;             PG8_LDA(At, 1, 1); PG8_STAGE(PG8_SB(1, 0), b3, voffB); PG8_STAGE(PG8_SB(1, 1), b3 + hstep, voffB); PG8_STAGE(PG8_SA(1, 0), a3, voffA);
;             PG8_WAIT_V(8); PG8_WAIT_L(0); PG8_BAR; PG8_MMA(1, 0, At, B0); PG8_MMA(1, 1, At, B1); PG8_BAR; PG8_SCHED;
	s_add_i32 s61, 0, 0x18000
	s_add_i32 s62, 0, 0x1c000
	s_add_u32 s36, s36, 0x40000
	s_addc_u32 s37, s37, 0
	s_mov_b32 m0, s47
	s_nop 0
	global_load_lds_dwordx4 v152, s[36:37]
	s_mov_b32 m0, s48
	s_nop 0
	global_load_lds_dwordx4 v156, s[36:37]
	v_add_u32_e32 v140, s61, v187
	v_add_u32_e32 v172, s62, v187
	ds_read_b128 v[128:131], v140
	ds_read_b128 v[132:135], v140 offset:1024
	ds_read_b128 v[136:139], v140 offset:2048
	ds_read_b128 v[140:143], v140 offset:3072
	ds_read_b128 v[144:147], v172
	ds_read_b128 v[148:151], v172 offset:1024
	ds_read_b128 v[168:171], v172 offset:2048
	ds_read_b128 v[172:175], v172 offset:3072
	ds_read_b128 v[176:179], v193 offset:32768
	ds_read_b128 v[180:183], v193 offset:33792
	ds_read_b128 v[194:197], v193 offset:34816
	ds_read_b128 v[198:201], v193 offset:35840
	ds_read_b128 v[202:205], v193 offset:36864
	ds_read_b128 v[206:209], v193 offset:37888
	ds_read_b128 v[210:213], v193 offset:38912
	ds_read_b128 v[214:217], v193 offset:39936
	s_waitcnt vmcnt(8)
	s_waitcnt lgkmcnt(0)
	s_barrier
	s_setprio 1
	v_mfma_f32_16x16x32_bf16 v[124:127], v[128:131], v[176:179], v[124:127]
	v_mfma_f32_16x16x32_bf16 v[120:123], v[136:139], v[176:179], v[120:123]
	v_mfma_f32_16x16x32_bf16 v[108:111], v[128:131], v[194:197], v[108:111]
	v_mfma_f32_16x16x32_bf16 v[104:107], v[136:139], v[194:197], v[104:107]
	v_mfma_f32_16x16x32_bf16 v[92:95], v[128:131], v[202:205], v[92:95]
	v_mfma_f32_16x16x32_bf16 v[88:91], v[136:139], v[202:205], v[88:91]
	v_mfma_f32_16x16x32_bf16 v[76:79], v[128:131], v[210:213], v[76:79]
	v_mfma_f32_16x16x32_bf16 v[72:75], v[136:139], v[210:213], v[72:75]
	v_mfma_f32_16x16x32_bf16 v[124:127], v[132:135], v[180:183], v[124:127]
	v_mfma_f32_16x16x32_bf16 v[120:123], v[140:143], v[180:183], v[120:123]
	v_mfma_f32_16x16x32_bf16 v[108:111], v[132:135], v[198:201], v[108:111]
	v_mfma_f32_16x16x32_bf16 v[104:107], v[140:143], v[198:201], v[104:107]
	v_mfma_f32_16x16x32_bf16 v[92:95], v[132:135], v[206:209], v[92:95]
	v_mfma_f32_16x16x32_bf16 v[88:91], v[140:143], v[206:209], v[88:91]
	v_mfma_f32_16x16x32_bf16 v[76:79], v[132:135], v[214:217], v[76:79]
	v_mfma_f32_16x16x32_bf16 v[72:75], v[140:143], v[214:217], v[72:75]
	v_mfma_f32_16x16x32_bf16 v[116:119], v[144:147], v[176:179], v[116:119]
	v_mfma_f32_16x16x32_bf16 v[112:115], v[168:171], v[176:179], v[112:115]
	v_mfma_f32_16x16x32_bf16 v[100:103], v[144:147], v[194:197], v[100:103]
	v_mfma_f32_16x16x32_bf16 v[96:99], v[168:171], v[194:197], v[96:99]
	v_mfma_f32_16x16x32_bf16 v[84:87], v[144:147], v[202:205], v[84:87]
	v_mfma_f32_16x16x32_bf16 v[80:83], v[168:171], v[202:205], v[80:83]
	v_mfma_f32_16x16x32_bf16 v[68:71], v[144:147], v[210:213], v[68:71]
	v_mfma_f32_16x16x32_bf16 v[64:67], v[168:171], v[210:213], v[64:67]
	v_mfma_f32_16x16x32_bf16 v[116:119], v[148:151], v[180:183], v[116:119]
	v_mfma_f32_16x16x32_bf16 v[112:115], v[172:175], v[180:183], v[112:115]
	v_mfma_f32_16x16x32_bf16 v[100:103], v[148:151], v[198:201], v[100:103]
	v_mfma_f32_16x16x32_bf16 v[96:99], v[172:175], v[198:201], v[96:99]
	v_mfma_f32_16x16x32_bf16 v[84:87], v[148:151], v[206:209], v[84:87]
	v_mfma_f32_16x16x32_bf16 v[80:83], v[172:175], v[206:209], v[80:83]
	v_mfma_f32_16x16x32_bf16 v[68:71], v[148:151], v[214:217], v[68:71]
	v_mfma_f32_16x16x32_bf16 v[64:67], v[172:175], v[214:217], v[64:67]
	s_setprio 0
	s_barrier
	s_add_i32 s36, s61, s0
	s_mov_b32 m0, s36
	ds_read_b128 v[176:179], v193 offset:49152
	global_load_lds_dwordx4 v154, s[98:99]
	s_add_i32 m0, s36, 0x2000
	s_add_u32 s34, s34, 0x40080
	s_addc_u32 s35, s35, 0
	s_add_i32 s36, s62, s0
	global_load_lds_dwordx4 v158, s[98:99]
	s_mov_b32 m0, s36
	ds_read_b128 v[180:183], v193 offset:50176
	global_load_lds_dwordx4 v154, s[34:35]
	s_add_i32 m0, s36, 0x2000
	ds_read_b128 v[194:197], v193 offset:51200
	global_load_lds_dwordx4 v158, s[34:35]
	s_mov_b32 m0, s50
	ds_read_b128 v[198:201], v193 offset:52224
	global_load_lds_dwordx4 v152, s[100:101]
	s_mov_b32 m0, s51
	ds_read_b128 v[202:205], v193 offset:53248
	global_load_lds_dwordx4 v156, s[100:101]
	ds_read_b128 v[206:209], v193 offset:54272
	ds_read_b128 v[210:213], v193 offset:55296
	ds_read_b128 v[214:217], v193 offset:56320
	s_waitcnt vmcnt(8)
	s_waitcnt lgkmcnt(0)
	s_barrier
	s_setprio 1
	v_mfma_f32_16x16x32_bf16 v[60:63], v[128:131], v[176:179], v[60:63]
	v_mfma_f32_16x16x32_bf16 v[56:59], v[136:139], v[176:179], v[56:59]
	v_mfma_f32_16x16x32_bf16 v[44:47], v[128:131], v[194:197], v[44:47]
	v_mfma_f32_16x16x32_bf16 v[40:43], v[136:139], v[194:197], v[40:43]
	v_mfma_f32_16x16x32_bf16 v[28:31], v[128:131], v[202:205], v[28:31]
	v_mfma_f32_16x16x32_bf16 v[24:27], v[136:139], v[202:205], v[24:27]
	v_mfma_f32_16x16x32_bf16 v[12:15], v[128:131], v[210:213], v[12:15]
	v_mfma_f32_16x16x32_bf16 v[8:11], v[136:139], v[210:213], v[8:11]
	v_mfma_f32_16x16x32_bf16 v[60:63], v[132:135], v[180:183], v[60:63]
	v_mfma_f32_16x16x32_bf16 v[56:59], v[140:143], v[180:183], v[56:59]
	v_mfma_f32_16x16x32_bf16 v[44:47], v[132:135], v[198:201], v[44:47]
	v_mfma_f32_16x16x32_bf16 v[40:43], v[140:143], v[198:201], v[40:43]
	v_mfma_f32_16x16x32_bf16 v[28:31], v[132:135], v[206:209], v[28:31]
	v_mfma_f32_16x16x32_bf16 v[24:27], v[140:143], v[206:209], v[24:27]
	v_mfma_f32_16x16x32_bf16 v[12:15], v[132:135], v[214:217], v[12:15]
	v_mfma_f32_16x16x32_bf16 v[8:11], v[140:143], v[214:217], v[8:11]
	v_mfma_f32_16x16x32_bf16 v[52:55], v[144:147], v[176:179], v[52:55]
	v_mfma_f32_16x16x32_bf16 v[48:51], v[168:171], v[176:179], v[48:51]
	v_mfma_f32_16x16x32_bf16 v[36:39], v[144:147], v[194:197], v[36:39]
	v_mfma_f32_16x16x32_bf16 v[32:35], v[168:171], v[194:197], v[32:35]
	v_mfma_f32_16x16x32_bf16 v[20:23], v[144:147], v[202:205], v[20:23]
	v_mfma_f32_16x16x32_bf16 v[16:19], v[168:171], v[202:205], v[16:19]
	v_mfma_f32_16x16x32_bf16 v[4:7], v[144:147], v[210:213], v[4:7]
	v_mfma_f32_16x16x32_bf16 v[0:3], v[168:171], v[210:213], v[0:3]
	v_mfma_f32_16x16x32_bf16 v[52:55], v[148:151], v[180:183], v[52:55]
	v_mfma_f32_16x16x32_bf16 v[48:51], v[172:175], v[180:183], v[48:51]
	v_mfma_f32_16x16x32_bf16 v[36:39], v[148:151], v[198:201], v[36:39]
	v_mfma_f32_16x16x32_bf16 v[32:35], v[172:175], v[198:201], v[32:35]
	v_mfma_f32_16x16x32_bf16 v[20:23], v[148:151], v[206:209], v[20:23]
	v_mfma_f32_16x16x32_bf16 v[16:19], v[172:175], v[206:209], v[16:19]
	v_mfma_f32_16x16x32_bf16 v[4:7], v[148:151], v[214:217], v[4:7]
	v_mfma_f32_16x16x32_bf16 v[0:3], v[172:175], v[214:217], v[0:3]
	s_setprio 0
	s_barrier
	s_add_i32 s60, s60, 2
	s_add_u32 s30, s30, 0x100
	s_addc_u32 s31, s31, 0
	s_add_u32 s58, s58, 0x100
	s_addc_u32 s59, s59, 0
	s_cmp_gt_u32 s60, 13
	s_cbranch_scc0 .LBB0_1148
	s_and_b64 vcc, exec, s[18:19]
	s_cbranch_vccz .LBB0_1151
	s_barrier

; #define PG8_STAGE(bufoff, gbase, voff) do { _Pragma("unroll") for (int _i = 0; _i < 2; ++_i) \
;         __builtin_amdgcn_global_load_lds((const unsigned*)((const char*)(gbase) + (voff)[_i]), (PG8_LAS unsigned*)(lds + (bufoff) + ldsw + _i * 8192), 16, 0, 0); } while (0)
; #define PG8_LDA(dst, b, h) do { _Pragma("unroll") for (int m = 0; m < 4; ++m) _Pragma("unroll") for (int k = 0; k < 2; ++k) dst[m][k] = *(const PG8_LAS bf16x8*)(lds + PG8_SA(b, h) + aoff + m * 2048 + k * 1024); } while (0)
; #define PG8_LDB(dst, b, h) do { _Pragma("unroll") for (int n = 0; n < 2; ++n) _Pragma("unroll") for (int k = 0; k < 2; ++k) dst[n][k] = *(const PG8_LAS bf16x8*)(lds + PG8_SB(b, h) + boff + n * 2048 + k * 1024); } while (0)
; #define PG8_MMA(ai, bj, At, Bt) do { __builtin_amdgcn_s_setprio(1); _Pragma("unroll") for (int m = 0; m < 4; ++m) _Pragma("unroll") for (int n = 0; n < 2; ++n) _Pragma("unroll") for (int k = 0; k < 2; ++k) \
;         acc[ai][bj][m][n] = __builtin_amdgcn_mfma_f32_16x16x32_bf16(Bt[n][k], At[m][k], acc[ai][bj][m][n], 0, 0, 0); __builtin_amdgcn_s_setprio(0); } while (0)
; #define PG8_WAIT_V(n) asm volatile("s_waitcnt vmcnt(" #n ")" ::: "memory")
; #define PG8_WAIT_L(n) asm volatile("s_waitcnt lgkmcnt(" #n ")" ::: "memory")
; template <class Epi, class Sched, bool ALIGN_EPI = false, bool SP2 = false>
; __device__ __forceinline__ void gemm_phase(PG8_LAS unsigned char* lds, const Gemm g, const Sched& S, const Epi& E, int tid_in) {
;     ...
;             const bool last = (t == nt - 2);
;             const char* a1 = cA + (size_t)(t + 1) * kstep;
;             const char* a2 = last ? nA : cA + (size_t)(t + 2) * kstep; const char* b2 = last ? nB : cB + (size_t)(t + 2) * kstep;
;             const char* a3 = a2 + kstep; const char* b3 = b2 + kstep;
;             if (last && has_next) S.a_ready(nxt);
;             if constexpr (SP2) {
;             PG8_LDB(B0, 0, 0); PG8_LDB(B1, 0, 1); PG8_SCHED; PG8_LDA(At, 0, 0); PG8_STAGE(PG8_SA(1, 1), a1 + hstep, voffA);
;             PG8_WAIT_V(8); PG8_WAIT_L(0); PG8_BAR; PG8_MMA(0, 0, At, B0); PG8_MMA(0, 1, At, B1); PG8_BAR; PG8_SCHED;
;             PG8_LDA(At, 0, 1); PG8_STAGE(PG8_SB(0, 0), b2, voffB); PG8_STAGE(PG8_SB(0, 1), b2 + hstep, voffB); PG8_STAGE(PG8_SA(0, 0), a2, voffA);
;             PG8_WAIT_V(8); PG8_WAIT_L(0); PG8_BAR; PG8_MMA(1, 0, At, B0); PG8_MMA(1, 1, At, B1); PG8_BAR; PG8_SCHED;
.LBB0_1238:
	s_add_u32 s26, s24, 0xfffc0080
	s_addc_u32 s27, s25, -1
	s_cmp_eq_u32 s58, 12
	s_cselect_b32 s29, s17, s27
	s_cselect_b32 s28, s54, s26
	s_cselect_b32 s27, s15, s57
	s_cselect_b32 s26, s55, s56
	s_add_i32 m0, s23, 0xc000
	ds_read_b128 v[144:147], v154
	global_load_lds_dwordx4 v136, s[24:25]
	s_add_i32 m0, s23, 0xe000
	ds_read_b128 v[158:161], v154 offset:1024
	global_load_lds_dwordx4 v138, s[24:25]
	ds_read_b128 v[162:165], v154 offset:2048
	ds_read_b128 v[166:169], v154 offset:3072
	ds_read_b128 v[170:173], v155
	ds_read_b128 v[174:177], v155 offset:1024
	ds_read_b128 v[178:181], v155 offset:2048
	ds_read_b128 v[182:185], v155 offset:3072
	ds_read_b128 v[186:189], v156
	ds_read_b128 v[190:193], v156 offset:1024
	ds_read_b128 v[194:197], v156 offset:2048
	ds_read_b128 v[198:201], v156 offset:3072
	ds_read_b128 v[202:205], v156 offset:4096
	ds_read_b128 v[206:209], v156 offset:5120
	ds_read_b128 v[210:213], v156 offset:6144
	ds_read_b128 v[214:217], v156 offset:7168
	s_waitcnt vmcnt(8)
	s_waitcnt lgkmcnt(0)
	s_barrier
	s_setprio 1
	v_mfma_f32_16x16x32_bf16 v[124:127], v[144:147], v[186:189], v[124:127]
	v_mfma_f32_16x16x32_bf16 v[120:123], v[162:165], v[186:189], v[120:123]
	v_mfma_f32_16x16x32_bf16 v[108:111], v[144:147], v[194:197], v[108:111]
	v_mfma_f32_16x16x32_bf16 v[104:107], v[162:165], v[194:197], v[104:107]
	v_mfma_f32_16x16x32_bf16 v[92:95], v[144:147], v[202:205], v[92:95]
	v_mfma_f32_16x16x32_bf16 v[88:91], v[162:165], v[202:205], v[88:91]
	v_mfma_f32_16x16x32_bf16 v[76:79], v[144:147], v[210:213], v[76:79]
	v_mfma_f32_16x16x32_bf16 v[72:75], v[162:165], v[210:213], v[72:75]
	v_mfma_f32_16x16x32_bf16 v[124:127], v[158:161], v[190:193], v[124:127]
	v_mfma_f32_16x16x32_bf16 v[120:123], v[166:169], v[190:193], v[120:123]
	v_mfma_f32_16x16x32_bf16 v[108:111], v[158:161], v[198:201], v[108:111]
	v_mfma_f32_16x16x32_bf16 v[104:107], v[166:169], v[198:201], v[104:107]
	v_mfma_f32_16x16x32_bf16 v[92:95], v[158:161], v[206:209], v[92:95]
	v_mfma_f32_16x16x32_bf16 v[88:91], v[166:169], v[206:209], v[88:91]
	v_mfma_f32_16x16x32_bf16 v[76:79], v[158:161], v[214:217], v[76:79]
	v_mfma_f32_16x16x32_bf16 v[72:75], v[166:169], v[214:217], v[72:75]
	v_mfma_f32_16x16x32_bf16 v[116:119], v[170:173], v[186:189], v[116:119]
	v_mfma_f32_16x16x32_bf16 v[112:115], v[178:181], v[186:189], v[112:115]
	v_mfma_f32_16x16x32_bf16 v[100:103], v[170:173], v[194:197], v[100:103]
	v_mfma_f32_16x16x32_bf16 v[96:99], v[178:181], v[194:197], v[96:99]
	v_mfma_f32_16x16x32_bf16 v[84:87], v[170:173], v[202:205], v[84:87]
	v_mfma_f32_16x16x32_bf16 v[80:83], v[178:181], v[202:205], v[80:83]
	v_mfma_f32_16x16x32_bf16 v[68:71], v[170:173], v[210:213], v[68:71]
	v_mfma_f32_16x16x32_bf16 v[64:67], v[178:181], v[210:213], v[64:67]
	v_mfma_f32_16x16x32_bf16 v[116:119], v[174:177], v[190:193], v[116:119]
	v_mfma_f32_16x16x32_bf16 v[112:115], v[182:185], v[190:193], v[112:115]
	v_mfma_f32_16x16x32_bf16 v[100:103], v[174:177], v[198:201], v[100:103]
	v_mfma_f32_16x16x32_bf16 v[96:99], v[182:185], v[198:201], v[96:99]
	v_mfma_f32_16x16x32_bf16 v[84:87], v[174:177], v[206:209], v[84:87]
	v_mfma_f32_16x16x32_bf16 v[80:83], v[182:185], v[206:209], v[80:83]
	v_mfma_f32_16x16x32_bf16 v[68:71], v[174:177], v[214:217], v[68:71]
	v_mfma_f32_16x16x32_bf16 v[64:67], v[182:185], v[214:217], v[64:67]
	s_setprio 0
	s_barrier
	s_add_u32 s98, s26, s10
	s_addc_u32 s99, s27, s11
	s_add_u32 s100, s28, s10
	s_addc_u32 s101, s29, s11
	s_add_i32 s59, s47, s0
	s_mov_b32 m0, s59
	ds_read_b128 v[186:189], v156 offset:16384
	global_load_lds_dwordx4 v132, s[26:27]
	s_add_i32 m0, s59, 0x2000
	s_add_u32 s60, s26, 0x40000
	s_addc_u32 s61, s27, 0
	s_add_i32 s59, s48, s0
	global_load_lds_dwordx4 v128, s[26:27]
	s_mov_b32 m0, s59
	ds_read_b128 v[190:193], v156 offset:17408
	global_load_lds_dwordx4 v132, s[60:61]
	s_add_i32 m0, s59, 0x2000
	ds_read_b128 v[194:197], v156 offset:18432
	global_load_lds_dwordx4 v128, s[60:61]
	s_mov_b32 m0, s23
	ds_read_b128 v[198:201], v156 offset:19456
	global_load_lds_dwordx4 v134, s[28:29]
	s_mov_b32 m0, s37
	ds_read_b128 v[202:205], v156 offset:20480
	global_load_lds_dwordx4 v130, s[28:29]
	ds_read_b128 v[206:209], v156 offset:21504
	ds_read_b128 v[210:213], v156 offset:22528
	ds_read_b128 v[214:217], v156 offset:23552
	s_waitcnt vmcnt(8)
	s_waitcnt lgkmcnt(0)
	s_barrier
	s_setprio 1
	v_mfma_f32_16x16x32_bf16 v[60:63], v[144:147], v[186:189], v[60:63]
	v_mfma_f32_16x16x32_bf16 v[56:59], v[162:165], v[186:189], v[56:59]
	v_mfma_f32_16x16x32_bf16 v[44:47], v[144:147], v[194:197], v[44:47]
	v_mfma_f32_16x16x32_bf16 v[40:43], v[162:165], v[194:197], v[40:43]
	v_mfma_f32_16x16x32_bf16 v[28:31], v[144:147], v[202:205], v[28:31]
	v_mfma_f32_16x16x32_bf16 v[24:27], v[162:165], v[202:205], v[24:27]
	v_mfma_f32_16x16x32_bf16 v[12:15], v[144:147], v[210:213], v[12:15]
	v_mfma_f32_16x16x32_bf16 v[8:11], v[162:165], v[210:213], v[8:11]
	v_mfma_f32_16x16x32_bf16 v[60:63], v[158:161], v[190:193], v[60:63]
	v_mfma_f32_16x16x32_bf16 v[56:59], v[166:169], v[190:193], v[56:59]
	v_mfma_f32_16x16x32_bf16 v[44:47], v[158:161], v[198:201], v[44:47]
	v_mfma_f32_16x16x32_bf16 v[40:43], v[166:169], v[198:201], v[40:43]
	v_mfma_f32_16x16x32_bf16 v[28:31], v[158:161], v[206:209], v[28:31]
	v_mfma_f32_16x16x32_bf16 v[24:27], v[166:169], v[206:209], v[24:27]
	v_mfma_f32_16x16x32_bf16 v[12:15], v[158:161], v[214:217], v[12:15]
	v_mfma_f32_16x16x32_bf16 v[8:11], v[166:169], v[214:217], v[8:11]
	v_mfma_f32_16x16x32_bf16 v[52:55], v[170:173], v[186:189], v[52:55]
	v_mfma_f32_16x16x32_bf16 v[48:51], v[178:181], v[186:189], v[48:51]
	v_mfma_f32_16x16x32_bf16 v[36:39], v[170:173], v[194:197], v[36:39]
	v_mfma_f32_16x16x32_bf16 v[32:35], v[178:181], v[194:197], v[32:35]
	v_mfma_f32_16x16x32_bf16 v[20:23], v[170:173], v[202:205], v[20:23]
	v_mfma_f32_16x16x32_bf16 v[16:19], v[178:181], v[202:205], v[16:19]
	v_mfma_f32_16x16x32_bf16 v[4:7], v[170:173], v[210:213], v[4:7]
	v_mfma_f32_16x16x32_bf16 v[0:3], v[178:181], v[210:213], v[0:3]
	v_mfma_f32_16x16x32_bf16 v[52:55], v[174:177], v[190:193], v[52:55]
	v_mfma_f32_16x16x32_bf16 v[48:51], v[182:185], v[190:193], v[48:51]
	v_mfma_f32_16x16x32_bf16 v[36:39], v[174:177], v[198:201], v[36:39]
	v_mfma_f32_16x16x32_bf16 v[32:35], v[182:185], v[198:201], v[32:35]
	v_mfma_f32_16x16x32_bf16 v[20:23], v[174:177], v[206:209], v[20:23]
	v_mfma_f32_16x16x32_bf16 v[16:19], v[182:185], v[206:209], v[16:19]
	v_mfma_f32_16x16x32_bf16 v[4:7], v[174:177], v[214:217], v[4:7]
	v_mfma_f32_16x16x32_bf16 v[0:3], v[182:185], v[214:217], v[0:3]
	s_setprio 0
	s_barrier
; #define PG8_STAGE(bufoff, gbase, voff) do { _Pragma("unroll") for (int _i = 0; _i < 2; ++_i) \
;         __builtin_amdgcn_global_load_lds((const unsigned*)((const char*)(gbase) + (voff)[_i]), (PG8_LAS unsigned*)(lds + (bufoff) + ldsw + _i * 8192), 16, 0, 0); } while (0)
; #define PG8_LDA(dst, b, h) do { _Pragma("unroll") for (int m = 0; m < 4; ++m) _Pragma("unroll") for (int k = 0; k < 2; ++k) dst[m][k] = *(const PG8_LAS bf16x8*)(lds + PG8_SA(b, h) + aoff + m * 2048 + k * 1024); } while (0)
; #define PG8_LDB(dst, b, h) do { _Pragma("unroll") for (int n = 0; n < 2; ++n) _Pragma("unroll") for (int k = 0; k < 2; ++k) dst[n][k] = *(const PG8_LAS bf16x8*)(lds + PG8_SB(b, h) + boff + n * 2048 + k * 1024); } while (0)
; #define PG8_MMA(ai, bj, At, Bt) do { __builtin_amdgcn_s_setprio(1); _Pragma("unroll") for (int m = 0; m < 4; ++m) _Pragma("unroll") for (int n = 0; n < 2; ++n) _Pragma("unroll") for (int k = 0; k < 2; ++k) \
;         acc[ai][bj][m][n] = __builtin_amdgcn_mfma_f32_16x16x32_bf16(Bt[n][k], At[m][k], acc[ai][bj][m][n], 0, 0, 0); __builtin_amdgcn_s_setprio(0); } while (0)
; #define PG8_WAIT_V(n) asm volatile("s_waitcnt vmcnt(" #n ")" ::: "memory")
; #define PG8_WAIT_L(n) asm volatile("s_waitcnt lgkmcnt(" #n ")" ::: "memory")
; #define PG8_BAR __builtin_amdgcn_s_barrier()
; #define PG8_SCHED __builtin_amdgcn_sched_barrier(0)
; template <class Epi, class Sched, bool ALIGN_EPI = false, bool SP2 = false>
; __device__ __forceinline__ void gemm_phase(PG8_LAS unsigned char* lds, const Gemm g, const Sched& S, const Epi& E, int tid_in) {
;     ...
;             PG8_LDB(B0, 1, 0); PG8_LDB(B1, 1, 1); PG8_SCHED; PG8_LDA(At, 1, 0); PG8_STAGE(PG8_SA(0, 1), a2 + hstep, voffA);
;             PG8_WAIT_V(8); PG8_WAIT_L(0); PG8_BAR; PG8_MMA(0, 0, At, B0); PG8_MMA(0, 1, At, B1); PG8_BAR; PG8_SCHED;
;             PG8_LDA(At, 1, 1); PG8_STAGE(PG8_SB(1, 0), b3, voffB); PG8_STAGE(PG8_SB(1, 1), b3 + hstep, voffB); PG8_STAGE(PG8_SA(1, 0), a3, voffA);
;             PG8_WAIT_V(8); PG8_WAIT_L(0); PG8_BAR; PG8_MMA(1, 0, At, B0); PG8_MMA(1, 1, At, B1); PG8_BAR; PG8_SCHED;
	s_add_i32 s59, 0, 0x18000
	s_add_i32 s60, 0, 0x1c000
	s_add_u32 s28, s28, 0x40000
	s_addc_u32 s29, s29, 0
	s_mov_b32 m0, s38
	v_add_u32_e32 v157, s59, v151
	global_load_lds_dwordx4 v134, s[28:29]
	s_mov_b32 m0, s39
	ds_read_b128 v[144:147], v157
	global_load_lds_dwordx4 v130, s[28:29]
	ds_read_b128 v[158:161], v157 offset:1024
	ds_read_b128 v[162:165], v157 offset:2048
	ds_read_b128 v[166:169], v157 offset:3072
	v_add_u32_e32 v157, s60, v151
	ds_read_b128 v[170:173], v157
	ds_read_b128 v[174:177], v157 offset:1024
	ds_read_b128 v[178:181], v157 offset:2048
	ds_read_b128 v[182:185], v157 offset:3072
	ds_read_b128 v[186:189], v156 offset:32768
	ds_read_b128 v[190:193], v156 offset:33792
	ds_read_b128 v[194:197], v156 offset:34816
	ds_read_b128 v[198:201], v156 offset:35840
	ds_read_b128 v[202:205], v156 offset:36864
	ds_read_b128 v[206:209], v156 offset:37888
	ds_read_b128 v[210:213], v156 offset:38912
	ds_read_b128 v[214:217], v156 offset:39936
	s_waitcnt vmcnt(8)
	s_waitcnt lgkmcnt(0)
	s_barrier
	s_setprio 1
	v_mfma_f32_16x16x32_bf16 v[124:127], v[144:147], v[186:189], v[124:127]
	v_mfma_f32_16x16x32_bf16 v[120:123], v[162:165], v[186:189], v[120:123]
	v_mfma_f32_16x16x32_bf16 v[108:111], v[144:147], v[194:197], v[108:111]
	v_mfma_f32_16x16x32_bf16 v[104:107], v[162:165], v[194:197], v[104:107]
	v_mfma_f32_16x16x32_bf16 v[92:95], v[144:147], v[202:205], v[92:95]
	v_mfma_f32_16x16x32_bf16 v[88:91], v[162:165], v[202:205], v[88:91]
	v_mfma_f32_16x16x32_bf16 v[76:79], v[144:147], v[210:213], v[76:79]
	v_mfma_f32_16x16x32_bf16 v[72:75], v[162:165], v[210:213], v[72:75]
	v_mfma_f32_16x16x32_bf16 v[124:127], v[158:161], v[190:193], v[124:127]
	v_mfma_f32_16x16x32_bf16 v[120:123], v[166:169], v[190:193], v[120:123]
	v_mfma_f32_16x16x32_bf16 v[108:111], v[158:161], v[198:201], v[108:111]
	v_mfma_f32_16x16x32_bf16 v[104:107], v[166:169], v[198:201], v[104:107]
	v_mfma_f32_16x16x32_bf16 v[92:95], v[158:161], v[206:209], v[92:95]
	v_mfma_f32_16x16x32_bf16 v[88:91], v[166:169], v[206:209], v[88:91]
	v_mfma_f32_16x16x32_bf16 v[76:79], v[158:161], v[214:217], v[76:79]
	v_mfma_f32_16x16x32_bf16 v[72:75], v[166:169], v[214:217], v[72:75]
	v_mfma_f32_16x16x32_bf16 v[116:119], v[170:173], v[186:189], v[116:119]
	v_mfma_f32_16x16x32_bf16 v[112:115], v[178:181], v[186:189], v[112:115]
	v_mfma_f32_16x16x32_bf16 v[100:103], v[170:173], v[194:197], v[100:103]
	v_mfma_f32_16x16x32_bf16 v[96:99], v[178:181], v[194:197], v[96:99]
	v_mfma_f32_16x16x32_bf16 v[84:87], v[170:173], v[202:205], v[84:87]
	v_mfma_f32_16x16x32_bf16 v[80:83], v[178:181], v[202:205], v[80:83]
	v_mfma_f32_16x16x32_bf16 v[68:71], v[170:173], v[210:213], v[68:71]
	v_mfma_f32_16x16x32_bf16 v[64:67], v[178:181], v[210:213], v[64:67]
	v_mfma_f32_16x16x32_bf16 v[116:119], v[174:177], v[190:193], v[116:119]
	v_mfma_f32_16x16x32_bf16 v[112:115], v[182:185], v[190:193], v[112:115]
	v_mfma_f32_16x16x32_bf16 v[100:103], v[174:177], v[198:201], v[100:103]
	v_mfma_f32_16x16x32_bf16 v[96:99], v[182:185], v[198:201], v[96:99]
	v_mfma_f32_16x16x32_bf16 v[84:87], v[174:177], v[206:209], v[84:87]
	v_mfma_f32_16x16x32_bf16 v[80:83], v[182:185], v[206:209], v[80:83]
	v_mfma_f32_16x16x32_bf16 v[68:71], v[174:177], v[214:217], v[68:71]
	v_mfma_f32_16x16x32_bf16 v[64:67], v[182:185], v[214:217], v[64:67]
	s_setprio 0
	s_barrier
	s_add_i32 s28, s59, s0
	s_mov_b32 m0, s28
	ds_read_b128 v[186:189], v156 offset:49152
	global_load_lds_dwordx4 v132, s[98:99]
	s_add_i32 m0, s28, 0x2000
	s_add_u32 s26, s26, 0x40080
	s_addc_u32 s27, s27, 0
	s_add_i32 s28, s60, s0
	global_load_lds_dwordx4 v128, s[98:99]
	s_mov_b32 m0, s28
	ds_read_b128 v[190:193], v156 offset:50176
	global_load_lds_dwordx4 v132, s[26:27]
	s_add_i32 m0, s28, 0x2000
	ds_read_b128 v[194:197], v156 offset:51200
	global_load_lds_dwordx4 v128, s[26:27]
	s_mov_b32 m0, s44
	ds_read_b128 v[198:201], v156 offset:52224
	global_load_lds_dwordx4 v134, s[100:101]
	s_mov_b32 m0, s45
	ds_read_b128 v[202:205], v156 offset:53248
	global_load_lds_dwordx4 v130, s[100:101]
	ds_read_b128 v[206:209], v156 offset:54272
	ds_read_b128 v[210:213], v156 offset:55296
	ds_read_b128 v[214:217], v156 offset:56320
	s_waitcnt vmcnt(8)
	s_waitcnt lgkmcnt(0)
	s_barrier
	s_setprio 1
	v_mfma_f32_16x16x32_bf16 v[60:63], v[144:147], v[186:189], v[60:63]
	v_mfma_f32_16x16x32_bf16 v[56:59], v[162:165], v[186:189], v[56:59]
	v_mfma_f32_16x16x32_bf16 v[44:47], v[144:147], v[194:197], v[44:47]
	v_mfma_f32_16x16x32_bf16 v[40:43], v[162:165], v[194:197], v[40:43]
	v_mfma_f32_16x16x32_bf16 v[28:31], v[144:147], v[202:205], v[28:31]
	v_mfma_f32_16x16x32_bf16 v[24:27], v[162:165], v[202:205], v[24:27]
	v_mfma_f32_16x16x32_bf16 v[12:15], v[144:147], v[210:213], v[12:15]
	v_mfma_f32_16x16x32_bf16 v[8:11], v[162:165], v[210:213], v[8:11]
	v_mfma_f32_16x16x32_bf16 v[60:63], v[158:161], v[190:193], v[60:63]
	v_mfma_f32_16x16x32_bf16 v[56:59], v[166:169], v[190:193], v[56:59]
	v_mfma_f32_16x16x32_bf16 v[44:47], v[158:161], v[198:201], v[44:47]
	v_mfma_f32_16x16x32_bf16 v[40:43], v[166:169], v[198:201], v[40:43]
	v_mfma_f32_16x16x32_bf16 v[28:31], v[158:161], v[206:209], v[28:31]
	v_mfma_f32_16x16x32_bf16 v[24:27], v[166:169], v[206:209], v[24:27]
	v_mfma_f32_16x16x32_bf16 v[12:15], v[158:161], v[214:217], v[12:15]
	v_mfma_f32_16x16x32_bf16 v[8:11], v[166:169], v[214:217], v[8:11]
	v_mfma_f32_16x16x32_bf16 v[52:55], v[170:173], v[186:189], v[52:55]
	v_mfma_f32_16x16x32_bf16 v[48:51], v[178:181], v[186:189], v[48:51]
	v_mfma_f32_16x16x32_bf16 v[36:39], v[170:173], v[194:197], v[36:39]
	v_mfma_f32_16x16x32_bf16 v[32:35], v[178:181], v[194:197], v[32:35]
	v_mfma_f32_16x16x32_bf16 v[20:23], v[170:173], v[202:205], v[20:23]
	v_mfma_f32_16x16x32_bf16 v[16:19], v[178:181], v[202:205], v[16:19]
	v_mfma_f32_16x16x32_bf16 v[4:7], v[170:173], v[210:213], v[4:7]
	v_mfma_f32_16x16x32_bf16 v[0:3], v[178:181], v[210:213], v[0:3]
	v_mfma_f32_16x16x32_bf16 v[52:55], v[174:177], v[190:193], v[52:55]
	v_mfma_f32_16x16x32_bf16 v[48:51], v[182:185], v[190:193], v[48:51]
	v_mfma_f32_16x16x32_bf16 v[36:39], v[174:177], v[198:201], v[36:39]
	v_mfma_f32_16x16x32_bf16 v[32:35], v[182:185], v[198:201], v[32:35]
	v_mfma_f32_16x16x32_bf16 v[20:23], v[174:177], v[206:209], v[20:23]
	v_mfma_f32_16x16x32_bf16 v[16:19], v[182:185], v[206:209], v[16:19]
	v_mfma_f32_16x16x32_bf16 v[4:7], v[174:177], v[214:217], v[4:7]
	v_mfma_f32_16x16x32_bf16 v[0:3], v[182:185], v[214:217], v[0:3]
	s_setprio 0
	s_barrier
	s_add_i32 s58, s58, 2
	s_add_u32 s24, s24, 0x100
	s_addc_u32 s25, s25, 0
	s_add_u32 s56, s56, 0x100
	s_addc_u32 s57, s57, 0
	s_cmp_gt_u32 s58, 13
	s_cbranch_scc0 .LBB0_1238
	s_and_b64 vcc, exec, s[12:13]
	s_cbranch_vccz .LBB0_1241
	s_barrier

; #define PG8_STAGE(bufoff, gbase, voff) do { _Pragma("unroll") for (int _i = 0; _i < 2; ++_i) \
;         __builtin_amdgcn_global_load_lds((const unsigned*)((const char*)(gbase) + (voff)[_i]), (PG8_LAS unsigned*)(lds + (bufoff) + ldsw + _i * 8192), 16, 0, 0); } while (0)
; #define PG8_LDA(dst, b, h) do { _Pragma("unroll") for (int m = 0; m < 4; ++m) _Pragma("unroll") for (int k = 0; k < 2; ++k) dst[m][k] = *(const PG8_LAS bf16x8*)(lds + PG8_SA(b, h) + aoff + m * 2048 + k * 1024); } while (0)
; #define PG8_LDB(dst, b, h) do { _Pragma("unroll") for (int n = 0; n < 2; ++n) _Pragma("unroll") for (int k = 0; k < 2; ++k) dst[n][k] = *(const PG8_LAS bf16x8*)(lds + PG8_SB(b, h) + boff + n * 2048 + k * 1024); } while (0)
; #define PG8_MMA(ai, bj, At, Bt) do { __builtin_amdgcn_s_setprio(1); _Pragma("unroll") for (int m = 0; m < 4; ++m) _Pragma("unroll") for (int n = 0; n < 2; ++n) _Pragma("unroll") for (int k = 0; k < 2; ++k) \
;         acc[ai][bj][m][n] = __builtin_amdgcn_mfma_f32_16x16x32_bf16(Bt[n][k], At[m][k], acc[ai][bj][m][n], 0, 0, 0); __builtin_amdgcn_s_setprio(0); } while (0)
; #define PG8_WAIT_V(n) asm volatile("s_waitcnt vmcnt(" #n ")" ::: "memory")
; #define PG8_WAIT_L(n) asm volatile("s_waitcnt lgkmcnt(" #n ")" ::: "memory")
; template <class Epi, class Sched, bool ALIGN_EPI = false, bool SP2 = false>
; __device__ __forceinline__ void gemm_phase(PG8_LAS unsigned char* lds, const Gemm g, const Sched& S, const Epi& E, int tid_in) {
;     ...
;             const bool last = (t == nt - 2);
;             const char* a1 = cA + (size_t)(t + 1) * kstep;
;             const char* a2 = last ? nA : cA + (size_t)(t + 2) * kstep; const char* b2 = last ? nB : cB + (size_t)(t + 2) * kstep;
;             const char* a3 = a2 + kstep; const char* b3 = b2 + kstep;
;             if (last && has_next) S.a_ready(nxt);
;             if constexpr (SP2) {
;             PG8_LDB(B0, 0, 0); PG8_LDB(B1, 0, 1); PG8_SCHED; PG8_LDA(At, 0, 0); PG8_STAGE(PG8_SA(1, 1), a1 + hstep, voffA);
;             PG8_WAIT_V(8); PG8_WAIT_L(0); PG8_BAR; PG8_MMA(0, 0, At, B0); PG8_MMA(0, 1, At, B1); PG8_BAR; PG8_SCHED;
;             PG8_LDA(At, 0, 1); PG8_STAGE(PG8_SB(0, 0), b2, voffB); PG8_STAGE(PG8_SB(0, 1), b2 + hstep, voffB); PG8_STAGE(PG8_SA(0, 0), a2, voffA);
;             PG8_WAIT_V(8); PG8_WAIT_L(0); PG8_BAR; PG8_MMA(1, 0, At, B0); PG8_MMA(1, 1, At, B1); PG8_BAR; PG8_SCHED;
.LBB0_1321:
	s_add_u32 s2, s20, 0x100
	s_addc_u32 s3, s21, 0
	s_cmp_eq_u32 s50, 40
	s_cselect_b32 s25, s17, s3
	s_cselect_b32 s24, s16, s2
	s_cselect_b32 s23, s19, s49
	s_cselect_b32 s22, s18, s48
	s_add_i32 m0, s34, 0xc000
	ds_read_b128 v[128:131], v195
	global_load_lds_dwordx4 v168, s[20:21]
	s_add_i32 m0, s34, 0xe000
	ds_read_b128 v[132:135], v195 offset:1024
	global_load_lds_dwordx4 v170, s[20:21]
	ds_read_b128 v[136:139], v195 offset:2048
	ds_read_b128 v[140:143], v195 offset:3072
	ds_read_b128 v[144:147], v196
	ds_read_b128 v[148:151], v196 offset:1024
	ds_read_b128 v[152:155], v196 offset:2048
	ds_read_b128 v[156:159], v196 offset:3072
	ds_read_b128 v[176:179], v197
	ds_read_b128 v[180:183], v197 offset:1024
	ds_read_b128 v[184:187], v197 offset:2048
	ds_read_b128 v[188:191], v197 offset:3072
	ds_read_b128 v[198:201], v197 offset:4096
	ds_read_b128 v[202:205], v197 offset:5120
	ds_read_b128 v[206:209], v197 offset:6144
	ds_read_b128 v[210:213], v197 offset:7168
	s_waitcnt vmcnt(8)
	s_waitcnt lgkmcnt(0)
	s_barrier
	s_setprio 1
	v_mfma_f32_16x16x32_bf16 v[120:123], v[128:131], v[176:179], v[120:123]
	v_mfma_f32_16x16x32_bf16 v[124:127], v[136:139], v[176:179], v[124:127]
	v_mfma_f32_16x16x32_bf16 v[104:107], v[128:131], v[184:187], v[104:107]
	v_mfma_f32_16x16x32_bf16 v[108:111], v[136:139], v[184:187], v[108:111]
	v_mfma_f32_16x16x32_bf16 v[88:91], v[128:131], v[198:201], v[88:91]
	v_mfma_f32_16x16x32_bf16 v[92:95], v[136:139], v[198:201], v[92:95]
	v_mfma_f32_16x16x32_bf16 v[72:75], v[128:131], v[206:209], v[72:75]
	v_mfma_f32_16x16x32_bf16 v[76:79], v[136:139], v[206:209], v[76:79]
	v_mfma_f32_16x16x32_bf16 v[120:123], v[132:135], v[180:183], v[120:123]
	v_mfma_f32_16x16x32_bf16 v[124:127], v[140:143], v[180:183], v[124:127]
	v_mfma_f32_16x16x32_bf16 v[104:107], v[132:135], v[188:191], v[104:107]
	v_mfma_f32_16x16x32_bf16 v[108:111], v[140:143], v[188:191], v[108:111]
	v_mfma_f32_16x16x32_bf16 v[88:91], v[132:135], v[202:205], v[88:91]
	v_mfma_f32_16x16x32_bf16 v[92:95], v[140:143], v[202:205], v[92:95]
	v_mfma_f32_16x16x32_bf16 v[72:75], v[132:135], v[210:213], v[72:75]
	v_mfma_f32_16x16x32_bf16 v[76:79], v[140:143], v[210:213], v[76:79]
	v_mfma_f32_16x16x32_bf16 v[112:115], v[144:147], v[176:179], v[112:115]
	v_mfma_f32_16x16x32_bf16 v[116:119], v[152:155], v[176:179], v[116:119]
	v_mfma_f32_16x16x32_bf16 v[96:99], v[144:147], v[184:187], v[96:99]
	v_mfma_f32_16x16x32_bf16 v[100:103], v[152:155], v[184:187], v[100:103]
	v_mfma_f32_16x16x32_bf16 v[80:83], v[144:147], v[198:201], v[80:83]
	v_mfma_f32_16x16x32_bf16 v[84:87], v[152:155], v[198:201], v[84:87]
	v_mfma_f32_16x16x32_bf16 v[64:67], v[144:147], v[206:209], v[64:67]
	v_mfma_f32_16x16x32_bf16 v[68:71], v[152:155], v[206:209], v[68:71]
	v_mfma_f32_16x16x32_bf16 v[112:115], v[148:151], v[180:183], v[112:115]
	v_mfma_f32_16x16x32_bf16 v[116:119], v[156:159], v[180:183], v[116:119]
	v_mfma_f32_16x16x32_bf16 v[96:99], v[148:151], v[188:191], v[96:99]
	v_mfma_f32_16x16x32_bf16 v[100:103], v[156:159], v[188:191], v[100:103]
	v_mfma_f32_16x16x32_bf16 v[80:83], v[148:151], v[202:205], v[80:83]
	v_mfma_f32_16x16x32_bf16 v[84:87], v[156:159], v[202:205], v[84:87]
	v_mfma_f32_16x16x32_bf16 v[64:67], v[148:151], v[210:213], v[64:67]
	v_mfma_f32_16x16x32_bf16 v[68:71], v[156:159], v[210:213], v[68:71]
	s_setprio 0
	s_barrier
	s_add_u32 s98, s22, s10
	s_addc_u32 s99, s23, s11
	s_add_u32 s100, s24, s10
	s_addc_u32 s101, s25, s11
	s_add_i32 s20, s42, s31
	s_mov_b32 m0, s20
	ds_read_b128 v[176:179], v197 offset:16384
	global_load_lds_dwordx4 v162, s[22:23]
	s_add_i32 m0, s20, 0x2000
	s_add_u32 s20, s22, 0xb0000
	s_addc_u32 s21, s23, 0
	s_add_i32 s51, s43, s31
	global_load_lds_dwordx4 v166, s[22:23]
	s_mov_b32 m0, s51
	ds_read_b128 v[180:183], v197 offset:17408
	global_load_lds_dwordx4 v162, s[20:21]
	s_add_i32 m0, s51, 0x2000
	ds_read_b128 v[184:187], v197 offset:18432
	global_load_lds_dwordx4 v166, s[20:21]
	s_mov_b32 m0, s34
	ds_read_b128 v[188:191], v197 offset:19456
	global_load_lds_dwordx4 v160, s[24:25]
	s_mov_b32 m0, s35
	ds_read_b128 v[198:201], v197 offset:20480
	global_load_lds_dwordx4 v164, s[24:25]
	ds_read_b128 v[202:205], v197 offset:21504
	ds_read_b128 v[206:209], v197 offset:22528
	ds_read_b128 v[210:213], v197 offset:23552
	s_waitcnt vmcnt(8)
	s_waitcnt lgkmcnt(0)
	s_barrier
	s_setprio 1
	v_mfma_f32_16x16x32_bf16 v[56:59], v[128:131], v[176:179], v[56:59]
	v_mfma_f32_16x16x32_bf16 v[60:63], v[136:139], v[176:179], v[60:63]
	v_mfma_f32_16x16x32_bf16 v[40:43], v[128:131], v[184:187], v[40:43]
	v_mfma_f32_16x16x32_bf16 v[44:47], v[136:139], v[184:187], v[44:47]
	v_mfma_f32_16x16x32_bf16 v[24:27], v[128:131], v[198:201], v[24:27]
	v_mfma_f32_16x16x32_bf16 v[28:31], v[136:139], v[198:201], v[28:31]
	v_mfma_f32_16x16x32_bf16 v[8:11], v[128:131], v[206:209], v[8:11]
	v_mfma_f32_16x16x32_bf16 v[12:15], v[136:139], v[206:209], v[12:15]
	v_mfma_f32_16x16x32_bf16 v[56:59], v[132:135], v[180:183], v[56:59]
	v_mfma_f32_16x16x32_bf16 v[60:63], v[140:143], v[180:183], v[60:63]
	v_mfma_f32_16x16x32_bf16 v[40:43], v[132:135], v[188:191], v[40:43]
	v_mfma_f32_16x16x32_bf16 v[44:47], v[140:143], v[188:191], v[44:47]
	v_mfma_f32_16x16x32_bf16 v[24:27], v[132:135], v[202:205], v[24:27]
	v_mfma_f32_16x16x32_bf16 v[28:31], v[140:143], v[202:205], v[28:31]
	v_mfma_f32_16x16x32_bf16 v[8:11], v[132:135], v[210:213], v[8:11]
	v_mfma_f32_16x16x32_bf16 v[12:15], v[140:143], v[210:213], v[12:15]
	v_mfma_f32_16x16x32_bf16 v[48:51], v[144:147], v[176:179], v[48:51]
	v_mfma_f32_16x16x32_bf16 v[52:55], v[152:155], v[176:179], v[52:55]
	v_mfma_f32_16x16x32_bf16 v[32:35], v[144:147], v[184:187], v[32:35]
	v_mfma_f32_16x16x32_bf16 v[36:39], v[152:155], v[184:187], v[36:39]
	v_mfma_f32_16x16x32_bf16 v[16:19], v[144:147], v[198:201], v[16:19]
	v_mfma_f32_16x16x32_bf16 v[20:23], v[152:155], v[198:201], v[20:23]
	v_mfma_f32_16x16x32_bf16 v[4:7], v[144:147], v[206:209], v[4:7]
	v_mfma_f32_16x16x32_bf16 v[0:3], v[152:155], v[206:209], v[0:3]
	v_mfma_f32_16x16x32_bf16 v[48:51], v[148:151], v[180:183], v[48:51]
	v_mfma_f32_16x16x32_bf16 v[52:55], v[156:159], v[180:183], v[52:55]
	v_mfma_f32_16x16x32_bf16 v[32:35], v[148:151], v[188:191], v[32:35]
	v_mfma_f32_16x16x32_bf16 v[36:39], v[156:159], v[188:191], v[36:39]
	v_mfma_f32_16x16x32_bf16 v[16:19], v[148:151], v[202:205], v[16:19]
	v_mfma_f32_16x16x32_bf16 v[20:23], v[156:159], v[202:205], v[20:23]
	v_mfma_f32_16x16x32_bf16 v[4:7], v[148:151], v[210:213], v[4:7]
	v_mfma_f32_16x16x32_bf16 v[0:3], v[156:159], v[210:213], v[0:3]
	s_setprio 0
	s_barrier
; #define PG8_STAGE(bufoff, gbase, voff) do { _Pragma("unroll") for (int _i = 0; _i < 2; ++_i) \
;         __builtin_amdgcn_global_load_lds((const unsigned*)((const char*)(gbase) + (voff)[_i]), (PG8_LAS unsigned*)(lds + (bufoff) + ldsw + _i * 8192), 16, 0, 0); } while (0)
; #define PG8_LDA(dst, b, h) do { _Pragma("unroll") for (int m = 0; m < 4; ++m) _Pragma("unroll") for (int k = 0; k < 2; ++k) dst[m][k] = *(const PG8_LAS bf16x8*)(lds + PG8_SA(b, h) + aoff + m * 2048 + k * 1024); } while (0)
; #define PG8_LDB(dst, b, h) do { _Pragma("unroll") for (int n = 0; n < 2; ++n) _Pragma("unroll") for (int k = 0; k < 2; ++k) dst[n][k] = *(const PG8_LAS bf16x8*)(lds + PG8_SB(b, h) + boff + n * 2048 + k * 1024); } while (0)
; #define PG8_MMA(ai, bj, At, Bt) do { __builtin_amdgcn_s_setprio(1); _Pragma("unroll") for (int m = 0; m < 4; ++m) _Pragma("unroll") for (int n = 0; n < 2; ++n) _Pragma("unroll") for (int k = 0; k < 2; ++k) \
;         acc[ai][bj][m][n] = __builtin_amdgcn_mfma_f32_16x16x32_bf16(Bt[n][k], At[m][k], acc[ai][bj][m][n], 0, 0, 0); __builtin_amdgcn_s_setprio(0); } while (0)
; #define PG8_WAIT_V(n) asm volatile("s_waitcnt vmcnt(" #n ")" ::: "memory")
; #define PG8_WAIT_L(n) asm volatile("s_waitcnt lgkmcnt(" #n ")" ::: "memory")
; #define PG8_BAR __builtin_amdgcn_s_barrier()
; #define PG8_SCHED __builtin_amdgcn_sched_barrier(0)
; template <class Epi, class Sched, bool ALIGN_EPI = false, bool SP2 = false>
; __device__ __forceinline__ void gemm_phase(PG8_LAS unsigned char* lds, const Gemm g, const Sched& S, const Epi& E, int tid_in) {
;     ...
;             PG8_LDB(B0, 1, 0); PG8_LDB(B1, 1, 1); PG8_SCHED; PG8_LDA(At, 1, 0); PG8_STAGE(PG8_SA(0, 1), a2 + hstep, voffA);
;             PG8_WAIT_V(8); PG8_WAIT_L(0); PG8_BAR; PG8_MMA(0, 0, At, B0); PG8_MMA(0, 1, At, B1); PG8_BAR; PG8_SCHED;
;             PG8_LDA(At, 1, 1); PG8_STAGE(PG8_SB(1, 0), b3, voffB); PG8_STAGE(PG8_SB(1, 1), b3 + hstep, voffB); PG8_STAGE(PG8_SA(1, 0), a3, voffA);
;             PG8_WAIT_V(8); PG8_WAIT_L(0); PG8_BAR; PG8_MMA(1, 0, At, B0); PG8_MMA(1, 1, At, B1); PG8_BAR; PG8_SCHED;
	s_add_i32 s51, 0, 0x18000
	s_add_i32 s52, 0, 0x1c000
	s_add_u32 s20, s24, 0xb0000
	s_addc_u32 s21, s25, 0
	s_mov_b32 m0, s36
	s_nop 0
	global_load_lds_dwordx4 v160, s[20:21]
	s_mov_b32 m0, s37
	s_nop 0
	global_load_lds_dwordx4 v164, s[20:21]
	v_add_u32_e32 v140, s51, v193
	v_add_u32_e32 v156, s52, v193
	ds_read_b128 v[128:131], v140
	ds_read_b128 v[132:135], v140 offset:1024
	ds_read_b128 v[136:139], v140 offset:2048
	ds_read_b128 v[140:143], v140 offset:3072
	ds_read_b128 v[144:147], v156
	ds_read_b128 v[148:151], v156 offset:1024
	ds_read_b128 v[152:155], v156 offset:2048
	ds_read_b128 v[156:159], v156 offset:3072
	ds_read_b128 v[176:179], v197 offset:32768
	ds_read_b128 v[180:183], v197 offset:33792
	ds_read_b128 v[184:187], v197 offset:34816
	ds_read_b128 v[188:191], v197 offset:35840
	ds_read_b128 v[198:201], v197 offset:36864
	ds_read_b128 v[202:205], v197 offset:37888
	ds_read_b128 v[206:209], v197 offset:38912
	ds_read_b128 v[210:213], v197 offset:39936
	s_waitcnt vmcnt(8)
	s_waitcnt lgkmcnt(0)
	s_barrier
	s_setprio 1
	v_mfma_f32_16x16x32_bf16 v[120:123], v[128:131], v[176:179], v[120:123]
	v_mfma_f32_16x16x32_bf16 v[124:127], v[136:139], v[176:179], v[124:127]
	v_mfma_f32_16x16x32_bf16 v[104:107], v[128:131], v[184:187], v[104:107]
	v_mfma_f32_16x16x32_bf16 v[108:111], v[136:139], v[184:187], v[108:111]
	v_mfma_f32_16x16x32_bf16 v[88:91], v[128:131], v[198:201], v[88:91]
	v_mfma_f32_16x16x32_bf16 v[92:95], v[136:139], v[198:201], v[92:95]
	v_mfma_f32_16x16x32_bf16 v[72:75], v[128:131], v[206:209], v[72:75]
	v_mfma_f32_16x16x32_bf16 v[76:79], v[136:139], v[206:209], v[76:79]
	v_mfma_f32_16x16x32_bf16 v[120:123], v[132:135], v[180:183], v[120:123]
	v_mfma_f32_16x16x32_bf16 v[124:127], v[140:143], v[180:183], v[124:127]
	v_mfma_f32_16x16x32_bf16 v[104:107], v[132:135], v[188:191], v[104:107]
	v_mfma_f32_16x16x32_bf16 v[108:111], v[140:143], v[188:191], v[108:111]
	v_mfma_f32_16x16x32_bf16 v[88:91], v[132:135], v[202:205], v[88:91]
	v_mfma_f32_16x16x32_bf16 v[92:95], v[140:143], v[202:205], v[92:95]
	v_mfma_f32_16x16x32_bf16 v[72:75], v[132:135], v[210:213], v[72:75]
	v_mfma_f32_16x16x32_bf16 v[76:79], v[140:143], v[210:213], v[76:79]
	v_mfma_f32_16x16x32_bf16 v[112:115], v[144:147], v[176:179], v[112:115]
	v_mfma_f32_16x16x32_bf16 v[116:119], v[152:155], v[176:179], v[116:119]
	v_mfma_f32_16x16x32_bf16 v[96:99], v[144:147], v[184:187], v[96:99]
	v_mfma_f32_16x16x32_bf16 v[100:103], v[152:155], v[184:187], v[100:103]
	v_mfma_f32_16x16x32_bf16 v[80:83], v[144:147], v[198:201], v[80:83]
	v_mfma_f32_16x16x32_bf16 v[84:87], v[152:155], v[198:201], v[84:87]
	v_mfma_f32_16x16x32_bf16 v[64:67], v[144:147], v[206:209], v[64:67]
	v_mfma_f32_16x16x32_bf16 v[68:71], v[152:155], v[206:209], v[68:71]
	v_mfma_f32_16x16x32_bf16 v[112:115], v[148:151], v[180:183], v[112:115]
	v_mfma_f32_16x16x32_bf16 v[116:119], v[156:159], v[180:183], v[116:119]
	v_mfma_f32_16x16x32_bf16 v[96:99], v[148:151], v[188:191], v[96:99]
	v_mfma_f32_16x16x32_bf16 v[100:103], v[156:159], v[188:191], v[100:103]
	v_mfma_f32_16x16x32_bf16 v[80:83], v[148:151], v[202:205], v[80:83]
	v_mfma_f32_16x16x32_bf16 v[84:87], v[156:159], v[202:205], v[84:87]
	v_mfma_f32_16x16x32_bf16 v[64:67], v[148:151], v[210:213], v[64:67]
	v_mfma_f32_16x16x32_bf16 v[68:71], v[156:159], v[210:213], v[68:71]
	s_setprio 0
	s_barrier
	s_add_i32 s20, s51, s31
	s_mov_b32 m0, s20
	ds_read_b128 v[176:179], v197 offset:49152
	global_load_lds_dwordx4 v162, s[98:99]
	s_add_i32 m0, s20, 0x2000
	s_add_u32 s20, s22, 0xb0080
	s_addc_u32 s21, s23, 0
	s_add_i32 s22, s52, s31
	global_load_lds_dwordx4 v166, s[98:99]
	s_mov_b32 m0, s22
	ds_read_b128 v[180:183], v197 offset:50176
	global_load_lds_dwordx4 v162, s[20:21]
	s_add_i32 m0, s22, 0x2000
	ds_read_b128 v[184:187], v197 offset:51200
	global_load_lds_dwordx4 v166, s[20:21]
	s_mov_b32 m0, s39
	ds_read_b128 v[188:191], v197 offset:52224
	global_load_lds_dwordx4 v160, s[100:101]
	s_mov_b32 m0, s40
	ds_read_b128 v[198:201], v197 offset:53248
	global_load_lds_dwordx4 v164, s[100:101]
	ds_read_b128 v[202:205], v197 offset:54272
	ds_read_b128 v[206:209], v197 offset:55296
	ds_read_b128 v[210:213], v197 offset:56320
	s_waitcnt vmcnt(8)
	s_waitcnt lgkmcnt(0)
	s_barrier
	s_setprio 1
	v_mfma_f32_16x16x32_bf16 v[56:59], v[128:131], v[176:179], v[56:59]
	v_mfma_f32_16x16x32_bf16 v[60:63], v[136:139], v[176:179], v[60:63]
	v_mfma_f32_16x16x32_bf16 v[40:43], v[128:131], v[184:187], v[40:43]
	v_mfma_f32_16x16x32_bf16 v[44:47], v[136:139], v[184:187], v[44:47]
	v_mfma_f32_16x16x32_bf16 v[24:27], v[128:131], v[198:201], v[24:27]
	v_mfma_f32_16x16x32_bf16 v[28:31], v[136:139], v[198:201], v[28:31]
	v_mfma_f32_16x16x32_bf16 v[8:11], v[128:131], v[206:209], v[8:11]
	v_mfma_f32_16x16x32_bf16 v[12:15], v[136:139], v[206:209], v[12:15]
	v_mfma_f32_16x16x32_bf16 v[56:59], v[132:135], v[180:183], v[56:59]
	v_mfma_f32_16x16x32_bf16 v[60:63], v[140:143], v[180:183], v[60:63]
	v_mfma_f32_16x16x32_bf16 v[40:43], v[132:135], v[188:191], v[40:43]
	v_mfma_f32_16x16x32_bf16 v[44:47], v[140:143], v[188:191], v[44:47]
	v_mfma_f32_16x16x32_bf16 v[24:27], v[132:135], v[202:205], v[24:27]
	v_mfma_f32_16x16x32_bf16 v[28:31], v[140:143], v[202:205], v[28:31]
	v_mfma_f32_16x16x32_bf16 v[8:11], v[132:135], v[210:213], v[8:11]
	v_mfma_f32_16x16x32_bf16 v[12:15], v[140:143], v[210:213], v[12:15]
	v_mfma_f32_16x16x32_bf16 v[48:51], v[144:147], v[176:179], v[48:51]
	v_mfma_f32_16x16x32_bf16 v[52:55], v[152:155], v[176:179], v[52:55]
	v_mfma_f32_16x16x32_bf16 v[32:35], v[144:147], v[184:187], v[32:35]
	v_mfma_f32_16x16x32_bf16 v[36:39], v[152:155], v[184:187], v[36:39]
	v_mfma_f32_16x16x32_bf16 v[16:19], v[144:147], v[198:201], v[16:19]
	v_mfma_f32_16x16x32_bf16 v[20:23], v[152:155], v[198:201], v[20:23]
	v_mfma_f32_16x16x32_bf16 v[4:7], v[144:147], v[206:209], v[4:7]
	v_mfma_f32_16x16x32_bf16 v[0:3], v[152:155], v[206:209], v[0:3]
	v_mfma_f32_16x16x32_bf16 v[48:51], v[148:151], v[180:183], v[48:51]
	v_mfma_f32_16x16x32_bf16 v[52:55], v[156:159], v[180:183], v[52:55]
	v_mfma_f32_16x16x32_bf16 v[32:35], v[148:151], v[188:191], v[32:35]
	v_mfma_f32_16x16x32_bf16 v[36:39], v[156:159], v[188:191], v[36:39]
	v_mfma_f32_16x16x32_bf16 v[16:19], v[148:151], v[202:205], v[16:19]
	v_mfma_f32_16x16x32_bf16 v[20:23], v[156:159], v[202:205], v[20:23]
	v_mfma_f32_16x16x32_bf16 v[4:7], v[148:151], v[210:213], v[4:7]
	v_mfma_f32_16x16x32_bf16 v[0:3], v[156:159], v[210:213], v[0:3]
	s_setprio 0
	s_barrier
	s_add_i32 s50, s50, 2
	s_add_u32 s48, s48, 0x100
	s_addc_u32 s49, s49, 0
	s_cmp_gt_u32 s50, 41
	s_mov_b64 s[20:21], s[2:3]
	s_cbranch_scc0 .LBB0_1321
	s_and_b64 vcc, exec, s[12:13]
	s_cbranch_vccz .LBB0_1324
	s_barrier
